# strategy 4b: all 64 per-segment s_setprio flips deleted from the four GEMM K-loops (timing-only edit), on top of the fused P9
# speedup vs baseline: 1.0153x; 1.0096x over previous
; #define PG8_STAGE(bufoff, gbase, voff) do { _Pragma("unroll") for (int _i = 0; _i < 2; ++_i) \
;         __builtin_amdgcn_global_load_lds((const unsigned*)((const char*)(gbase) + (voff)[_i]), (PG8_LAS unsigned*)(lds + (bufoff) + ldsw + _i * 8192), 16, 0, 0); } while (0)
; #define PG8_LDA(dst, b, h) do { _Pragma("unroll") for (int m = 0; m < 4; ++m) _Pragma("unroll") for (int k = 0; k < 2; ++k) dst[m][k] = *(const PG8_LAS bf16x8*)(lds + PG8_SA(b, h) + aoff + m * 2048 + k * 1024); } while (0)
; #define PG8_LDB(dst, b, h) do { _Pragma("unroll") for (int n = 0; n < 2; ++n) _Pragma("unroll") for (int k = 0; k < 2; ++k) dst[n][k] = *(const PG8_LAS bf16x8*)(lds + PG8_SB(b, h) + boff + n * 2048 + k * 1024); } while (0)
; template <class Epi, class Sched, bool ALIGN_EPI = false, bool SP2 = false>
; __device__ __forceinline__ void gemm_phase(PG8_LAS unsigned char* lds, const Gemm g, const Sched& S, const Epi& E) {
;     ...
;         for (int t = 0; t < nt; t += 2) {
;             const bool last = (t == nt - 2);
;             const char* a1 = cA + (size_t)(t + 1) * kstep;
;             const char* a2 = last ? nA : cA + (size_t)(t + 2) * kstep; const char* b2 = last ? nB : cB + (size_t)(t + 2) * kstep;
;             const char* a3 = a2 + kstep; const char* b3 = b2 + kstep;
;             if (last && has_next) S.a_ready(nxt);
;             if constexpr (SP2) {
;             PG8_LDB(B0, 0, 0); PG8_LDB(B1, 0, 1); PG8_SCHED; PG8_LDA(At, 0, 0); PG8_STAGE(PG8_SA(1, 1), a1 + hstep, voffA);
;             PG8_WAIT_V(8); PG8_WAIT_L(0); PG8_BAR; PG8_MMA(0, 0, At, B0); PG8_MMA(0, 1, At, B1); PG8_BAR; PG8_SCHED;
;             PG8_LDA(At, 0, 1); PG8_STAGE(PG8_SB(0, 0), b2, voffB); PG8_STAGE(PG8_SB(0, 1), b2 + hstep, voffB); PG8_STAGE(PG8_SA(0, 0), a2, voffA);
;             PG8_WAIT_V(8); PG8_WAIT_L(0); PG8_BAR; PG8_MMA(1, 0, At, B0); PG8_MMA(1, 1, At, B1); PG8_BAR; PG8_SCHED;
;             PG8_LDB(B0, 1, 0); PG8_LDB(B1, 1, 1); PG8_SCHED; PG8_LDA(At, 1, 0); PG8_STAGE(PG8_SA(0, 1), a2 + hstep, voffA);
;             PG8_WAIT_V(8); PG8_WAIT_L(0); PG8_BAR; PG8_MMA(0, 0, At, B0); PG8_MMA(0, 1, At, B1); PG8_BAR; PG8_SCHED;
;             PG8_LDA(At, 1, 1); PG8_STAGE(PG8_SB(1, 0), b3, voffB); PG8_STAGE(PG8_SB(1, 1), b3 + hstep, voffB); PG8_STAGE(PG8_SA(1, 0), a3, voffA);
;             PG8_WAIT_V(8); PG8_WAIT_L(0); PG8_BAR; PG8_MMA(1, 0, At, B0); PG8_MMA(1, 1, At, B1); PG8_BAR; PG8_SCHED;
.LBB0_68:
	ds_read_b128 v[128:131], v203
	ds_read_b128 v[132:135], v203 offset:1024
	ds_read_b128 v[136:139], v203 offset:2048
	ds_read_b128 v[140:143], v203 offset:3072
	ds_read_b128 v[144:147], v204
	ds_read_b128 v[148:151], v204 offset:1024
	ds_read_b128 v[180:183], v204 offset:2048
	ds_read_b128 v[184:187], v204 offset:3072
	s_add_u32 s30, s82, 0xfff80080
	s_addc_u32 s31, s83, -1
	s_cmp_eq_u32 s29, 28
	s_cselect_b32 s87, s1, s31
	s_cselect_b32 s86, s75, s30
	s_cselect_b32 s85, s73, vcc_hi
	s_cselect_b32 s84, s81, vcc_lo
	s_add_i32 m0, s94, 0xc000
	ds_read_b128 v[206:209], v205
	ds_read_b128 v[210:213], v205 offset:1024
	ds_read_b128 v[214:217], v205 offset:2048
	ds_read_b128 v[218:221], v205 offset:3072
	ds_read_b128 v[222:225], v205 offset:4096
	ds_read_b128 v[226:229], v205 offset:5120
	ds_read_b128 v[230:233], v205 offset:6144
	ds_read_b128 v[234:237], v205 offset:7168
	global_load_lds_dwordx4 v170, s[82:83]
	s_add_i32 m0, s94, 0xe000
	s_nop 0
	global_load_lds_dwordx4 v172, s[82:83]
	s_waitcnt vmcnt(8)
	s_waitcnt lgkmcnt(0)
	s_barrier
	s_waitcnt lgkmcnt(0)
	v_mfma_f32_16x16x32_bf16 v[124:127], v[128:131], v[206:209], v[124:127]
	v_mfma_f32_16x16x32_bf16 v[120:123], v[136:139], v[206:209], v[120:123]
	v_mfma_f32_16x16x32_bf16 v[116:119], v[128:131], v[214:217], v[116:119]
	v_mfma_f32_16x16x32_bf16 v[112:115], v[136:139], v[214:217], v[112:115]
	v_mfma_f32_16x16x32_bf16 v[108:111], v[128:131], v[222:225], v[108:111]
	v_mfma_f32_16x16x32_bf16 v[104:107], v[136:139], v[222:225], v[104:107]
	v_mfma_f32_16x16x32_bf16 v[100:103], v[128:131], v[230:233], v[100:103]
	v_mfma_f32_16x16x32_bf16 v[96:99], v[136:139], v[230:233], v[96:99]
	v_mfma_f32_16x16x32_bf16 v[124:127], v[132:135], v[210:213], v[124:127]
	v_mfma_f32_16x16x32_bf16 v[120:123], v[140:143], v[210:213], v[120:123]
	v_mfma_f32_16x16x32_bf16 v[116:119], v[132:135], v[218:221], v[116:119]
	v_mfma_f32_16x16x32_bf16 v[112:115], v[140:143], v[218:221], v[112:115]
	v_mfma_f32_16x16x32_bf16 v[108:111], v[132:135], v[226:229], v[108:111]
	v_mfma_f32_16x16x32_bf16 v[104:107], v[140:143], v[226:229], v[104:107]
	v_mfma_f32_16x16x32_bf16 v[100:103], v[132:135], v[234:237], v[100:103]
	v_mfma_f32_16x16x32_bf16 v[96:99], v[140:143], v[234:237], v[96:99]
	v_mfma_f32_16x16x32_bf16 v[68:71], v[144:147], v[206:209], v[68:71]
	v_mfma_f32_16x16x32_bf16 v[64:67], v[180:183], v[206:209], v[64:67]
	v_mfma_f32_16x16x32_bf16 v[52:55], v[144:147], v[214:217], v[52:55]
	v_mfma_f32_16x16x32_bf16 v[48:51], v[180:183], v[214:217], v[48:51]
	v_mfma_f32_16x16x32_bf16 v[44:47], v[144:147], v[222:225], v[44:47]
	v_mfma_f32_16x16x32_bf16 v[40:43], v[180:183], v[222:225], v[40:43]
	v_mfma_f32_16x16x32_bf16 v[36:39], v[144:147], v[230:233], v[36:39]
	v_mfma_f32_16x16x32_bf16 v[32:35], v[180:183], v[230:233], v[32:35]
	v_mfma_f32_16x16x32_bf16 v[68:71], v[148:151], v[210:213], v[68:71]
	v_mfma_f32_16x16x32_bf16 v[64:67], v[184:187], v[210:213], v[64:67]
	v_mfma_f32_16x16x32_bf16 v[52:55], v[148:151], v[218:221], v[52:55]
	v_mfma_f32_16x16x32_bf16 v[48:51], v[184:187], v[218:221], v[48:51]
	v_mfma_f32_16x16x32_bf16 v[44:47], v[148:151], v[226:229], v[44:47]
	v_mfma_f32_16x16x32_bf16 v[40:43], v[184:187], v[226:229], v[40:43]
	v_mfma_f32_16x16x32_bf16 v[36:39], v[148:151], v[234:237], v[36:39]
	v_mfma_f32_16x16x32_bf16 v[32:35], v[184:187], v[234:237], v[32:35]
	s_barrier
	s_add_i32 s30, s47, s92
	s_mov_b32 m0, s30
	ds_read_b128 v[206:209], v205 offset:16384
	ds_read_b128 v[210:213], v205 offset:17408
	ds_read_b128 v[214:217], v205 offset:18432
	ds_read_b128 v[218:221], v205 offset:19456
	ds_read_b128 v[222:225], v205 offset:20480
	ds_read_b128 v[226:229], v205 offset:21504
	ds_read_b128 v[230:233], v205 offset:22528
	ds_read_b128 v[234:237], v205 offset:23552
	global_load_lds_dwordx4 v158, s[84:85]
	s_add_i32 m0, s30, 0x2000
	s_add_u32 s30, s84, 0x80000
	s_addc_u32 s31, s85, 0
	s_add_i32 s89, s33, s92
	global_load_lds_dwordx4 v154, s[84:85]
	s_mov_b32 m0, s89
	s_nop 0
	global_load_lds_dwordx4 v158, s[30:31]
	s_add_i32 m0, s89, 0x2000
	s_nop 0
	global_load_lds_dwordx4 v154, s[30:31]
	s_mov_b32 m0, s94
	s_nop 0
	global_load_lds_dwordx4 v160, s[86:87]
	s_mov_b32 m0, s95
	s_nop 0
	global_load_lds_dwordx4 v156, s[86:87]
	s_waitcnt vmcnt(8)
	s_waitcnt lgkmcnt(0)
	s_barrier
	s_waitcnt lgkmcnt(0)
	v_mfma_f32_16x16x32_bf16 v[92:95], v[128:131], v[206:209], v[92:95]
	v_mfma_f32_16x16x32_bf16 v[88:91], v[136:139], v[206:209], v[88:91]
	v_mfma_f32_16x16x32_bf16 v[84:87], v[128:131], v[214:217], v[84:87]
	v_mfma_f32_16x16x32_bf16 v[80:83], v[136:139], v[214:217], v[80:83]
	v_mfma_f32_16x16x32_bf16 v[76:79], v[128:131], v[222:225], v[76:79]
	v_mfma_f32_16x16x32_bf16 v[72:75], v[136:139], v[222:225], v[72:75]
	v_mfma_f32_16x16x32_bf16 v[60:63], v[128:131], v[230:233], v[60:63]
	v_mfma_f32_16x16x32_bf16 v[56:59], v[136:139], v[230:233], v[56:59]
	v_mfma_f32_16x16x32_bf16 v[92:95], v[132:135], v[210:213], v[92:95]
	v_mfma_f32_16x16x32_bf16 v[88:91], v[140:143], v[210:213], v[88:91]
	v_mfma_f32_16x16x32_bf16 v[84:87], v[132:135], v[218:221], v[84:87]
	v_mfma_f32_16x16x32_bf16 v[80:83], v[140:143], v[218:221], v[80:83]
	v_mfma_f32_16x16x32_bf16 v[76:79], v[132:135], v[226:229], v[76:79]
	v_mfma_f32_16x16x32_bf16 v[72:75], v[140:143], v[226:229], v[72:75]
	v_mfma_f32_16x16x32_bf16 v[60:63], v[132:135], v[234:237], v[60:63]
	v_mfma_f32_16x16x32_bf16 v[56:59], v[140:143], v[234:237], v[56:59]
	v_mfma_f32_16x16x32_bf16 v[28:31], v[144:147], v[206:209], v[28:31]
	v_mfma_f32_16x16x32_bf16 v[24:27], v[180:183], v[206:209], v[24:27]
	v_mfma_f32_16x16x32_bf16 v[20:23], v[144:147], v[214:217], v[20:23]
	v_mfma_f32_16x16x32_bf16 v[16:19], v[180:183], v[214:217], v[16:19]
	v_mfma_f32_16x16x32_bf16 v[12:15], v[144:147], v[222:225], v[12:15]
	v_mfma_f32_16x16x32_bf16 v[8:11], v[180:183], v[222:225], v[8:11]
	v_mfma_f32_16x16x32_bf16 v[4:7], v[144:147], v[230:233], v[4:7]
	v_mfma_f32_16x16x32_bf16 v[0:3], v[180:183], v[230:233], v[0:3]
	v_mfma_f32_16x16x32_bf16 v[28:31], v[148:151], v[210:213], v[28:31]
	v_mfma_f32_16x16x32_bf16 v[24:27], v[184:187], v[210:213], v[24:27]
	v_mfma_f32_16x16x32_bf16 v[20:23], v[148:151], v[218:221], v[20:23]
	v_mfma_f32_16x16x32_bf16 v[16:19], v[184:187], v[218:221], v[16:19]
	v_mfma_f32_16x16x32_bf16 v[12:15], v[148:151], v[226:229], v[12:15]
	v_mfma_f32_16x16x32_bf16 v[8:11], v[184:187], v[226:229], v[8:11]
	v_mfma_f32_16x16x32_bf16 v[4:7], v[148:151], v[234:237], v[4:7]
	v_mfma_f32_16x16x32_bf16 v[0:3], v[184:187], v[234:237], v[0:3]
	s_barrier
; #define PG8_STAGE(bufoff, gbase, voff) do { _Pragma("unroll") for (int _i = 0; _i < 2; ++_i) \
;         __builtin_amdgcn_global_load_lds((const unsigned*)((const char*)(gbase) + (voff)[_i]), (PG8_LAS unsigned*)(lds + (bufoff) + ldsw + _i * 8192), 16, 0, 0); } while (0)
; #define PG8_LDA(dst, b, h) do { _Pragma("unroll") for (int m = 0; m < 4; ++m) _Pragma("unroll") for (int k = 0; k < 2; ++k) dst[m][k] = *(const PG8_LAS bf16x8*)(lds + PG8_SA(b, h) + aoff + m * 2048 + k * 1024); } while (0)
; #define PG8_LDB(dst, b, h) do { _Pragma("unroll") for (int n = 0; n < 2; ++n) _Pragma("unroll") for (int k = 0; k < 2; ++k) dst[n][k] = *(const PG8_LAS bf16x8*)(lds + PG8_SB(b, h) + boff + n * 2048 + k * 1024); } while (0)
; template <class Epi, class Sched, bool ALIGN_EPI = false, bool SP2 = false>
; __device__ __forceinline__ void gemm_phase(PG8_LAS unsigned char* lds, const Gemm g, const Sched& S, const Epi& E) {
;     ...
;         for (int t = 0; t < nt; t += 2) {
;             const bool last = (t == nt - 2);
;             const char* a1 = cA + (size_t)(t + 1) * kstep;
;             const char* a2 = last ? nA : cA + (size_t)(t + 2) * kstep; const char* b2 = last ? nB : cB + (size_t)(t + 2) * kstep;
;             const char* a3 = a2 + kstep; const char* b3 = b2 + kstep;
;             if (last && has_next) S.a_ready(nxt);
;             if constexpr (SP2) {
;             PG8_LDB(B0, 0, 0); PG8_LDB(B1, 0, 1); PG8_SCHED; PG8_LDA(At, 0, 0); PG8_STAGE(PG8_SA(1, 1), a1 + hstep, voffA);
;             PG8_WAIT_V(8); PG8_WAIT_L(0); PG8_BAR; PG8_MMA(0, 0, At, B0); PG8_MMA(0, 1, At, B1); PG8_BAR; PG8_SCHED;
;             PG8_LDA(At, 0, 1); PG8_STAGE(PG8_SB(0, 0), b2, voffB); PG8_STAGE(PG8_SB(0, 1), b2 + hstep, voffB); PG8_STAGE(PG8_SA(0, 0), a2, voffA);
;             PG8_WAIT_V(8); PG8_WAIT_L(0); PG8_BAR; PG8_MMA(1, 0, At, B0); PG8_MMA(1, 1, At, B1); PG8_BAR; PG8_SCHED;
;             PG8_LDB(B0, 1, 0); PG8_LDB(B1, 1, 1); PG8_SCHED; PG8_LDA(At, 1, 0); PG8_STAGE(PG8_SA(0, 1), a2 + hstep, voffA);
;             PG8_WAIT_V(8); PG8_WAIT_L(0); PG8_BAR; PG8_MMA(0, 0, At, B0); PG8_MMA(0, 1, At, B1); PG8_BAR; PG8_SCHED;
;             PG8_LDA(At, 1, 1); PG8_STAGE(PG8_SB(1, 0), b3, voffB); PG8_STAGE(PG8_SB(1, 1), b3 + hstep, voffB); PG8_STAGE(PG8_SA(1, 0), a3, voffA);
;             PG8_WAIT_V(8); PG8_WAIT_L(0); PG8_BAR; PG8_MMA(1, 0, At, B0); PG8_MMA(1, 1, At, B1); PG8_BAR; PG8_SCHED;
	s_add_i32 s89, 0, 0x18000
	s_add_i32 s54, 0, 0x1c000
	v_add_u32_e32 v140, s89, v190
	v_add_u32_e32 v162, s54, v190
	ds_read_b128 v[128:131], v140
	ds_read_b128 v[132:135], v140 offset:1024
	ds_read_b128 v[136:139], v140 offset:2048
	ds_read_b128 v[140:143], v140 offset:3072
	ds_read_b128 v[144:147], v162
	ds_read_b128 v[148:151], v162 offset:1024
	ds_read_b128 v[180:183], v162 offset:2048
	ds_read_b128 v[184:187], v162 offset:3072
	s_add_u32 s30, s86, 0x80000
	s_addc_u32 s31, s87, 0
	s_mov_b32 m0, s96
	ds_read_b128 v[206:209], v205 offset:32768
	ds_read_b128 v[210:213], v205 offset:33792
	ds_read_b128 v[214:217], v205 offset:34816
	ds_read_b128 v[218:221], v205 offset:35840
	ds_read_b128 v[222:225], v205 offset:36864
	ds_read_b128 v[226:229], v205 offset:37888
	ds_read_b128 v[230:233], v205 offset:38912
	ds_read_b128 v[234:237], v205 offset:39936
	global_load_lds_dwordx4 v160, s[30:31]
	s_mov_b32 m0, s97
	s_nop 0
	global_load_lds_dwordx4 v156, s[30:31]
	s_waitcnt vmcnt(8)
	s_waitcnt lgkmcnt(0)
	s_barrier
	s_waitcnt lgkmcnt(0)
	v_mfma_f32_16x16x32_bf16 v[124:127], v[128:131], v[206:209], v[124:127]
	v_mfma_f32_16x16x32_bf16 v[120:123], v[136:139], v[206:209], v[120:123]
	v_mfma_f32_16x16x32_bf16 v[116:119], v[128:131], v[214:217], v[116:119]
	v_mfma_f32_16x16x32_bf16 v[112:115], v[136:139], v[214:217], v[112:115]
	v_mfma_f32_16x16x32_bf16 v[108:111], v[128:131], v[222:225], v[108:111]
	v_mfma_f32_16x16x32_bf16 v[104:107], v[136:139], v[222:225], v[104:107]
	v_mfma_f32_16x16x32_bf16 v[100:103], v[128:131], v[230:233], v[100:103]
	v_mfma_f32_16x16x32_bf16 v[96:99], v[136:139], v[230:233], v[96:99]
	v_mfma_f32_16x16x32_bf16 v[124:127], v[132:135], v[210:213], v[124:127]
	v_mfma_f32_16x16x32_bf16 v[120:123], v[140:143], v[210:213], v[120:123]
	v_mfma_f32_16x16x32_bf16 v[116:119], v[132:135], v[218:221], v[116:119]
	v_mfma_f32_16x16x32_bf16 v[112:115], v[140:143], v[218:221], v[112:115]
	v_mfma_f32_16x16x32_bf16 v[108:111], v[132:135], v[226:229], v[108:111]
	v_mfma_f32_16x16x32_bf16 v[104:107], v[140:143], v[226:229], v[104:107]
	v_mfma_f32_16x16x32_bf16 v[100:103], v[132:135], v[234:237], v[100:103]
	v_mfma_f32_16x16x32_bf16 v[96:99], v[140:143], v[234:237], v[96:99]
	v_mfma_f32_16x16x32_bf16 v[68:71], v[144:147], v[206:209], v[68:71]
	v_mfma_f32_16x16x32_bf16 v[64:67], v[180:183], v[206:209], v[64:67]
	v_mfma_f32_16x16x32_bf16 v[52:55], v[144:147], v[214:217], v[52:55]
	v_mfma_f32_16x16x32_bf16 v[48:51], v[180:183], v[214:217], v[48:51]
	v_mfma_f32_16x16x32_bf16 v[44:47], v[144:147], v[222:225], v[44:47]
	v_mfma_f32_16x16x32_bf16 v[40:43], v[180:183], v[222:225], v[40:43]
	v_mfma_f32_16x16x32_bf16 v[36:39], v[144:147], v[230:233], v[36:39]
	v_mfma_f32_16x16x32_bf16 v[32:35], v[180:183], v[230:233], v[32:35]
	v_mfma_f32_16x16x32_bf16 v[68:71], v[148:151], v[210:213], v[68:71]
	v_mfma_f32_16x16x32_bf16 v[64:67], v[184:187], v[210:213], v[64:67]
	v_mfma_f32_16x16x32_bf16 v[52:55], v[148:151], v[218:221], v[52:55]
	v_mfma_f32_16x16x32_bf16 v[48:51], v[184:187], v[218:221], v[48:51]
	v_mfma_f32_16x16x32_bf16 v[44:47], v[148:151], v[226:229], v[44:47]
	v_mfma_f32_16x16x32_bf16 v[40:43], v[184:187], v[226:229], v[40:43]
	v_mfma_f32_16x16x32_bf16 v[36:39], v[148:151], v[234:237], v[36:39]
	v_mfma_f32_16x16x32_bf16 v[32:35], v[184:187], v[234:237], v[32:35]
	s_barrier
	s_add_i32 s30, s89, s92
	s_mov_b32 m0, s30
	ds_read_b128 v[206:209], v205 offset:49152
	ds_read_b128 v[210:213], v205 offset:50176
	ds_read_b128 v[214:217], v205 offset:51200
	ds_read_b128 v[218:221], v205 offset:52224
	ds_read_b128 v[222:225], v205 offset:53248
	ds_read_b128 v[226:229], v205 offset:54272
	ds_read_b128 v[230:233], v205 offset:55296
	ds_read_b128 v[234:237], v205 offset:56320
	s_add_u32 s62, s84, 0x80
	s_addc_u32 s63, s85, 0
	global_load_lds_dwordx4 v158, s[62:63]
	s_add_i32 m0, s30, 0x2000
	s_add_u32 s30, s84, 0x80080
	s_addc_u32 s31, s85, 0
	s_add_i32 s54, s54, s92
	global_load_lds_dwordx4 v154, s[62:63]
	s_mov_b32 m0, s54
	s_nop 0
	global_load_lds_dwordx4 v158, s[30:31]
	s_add_i32 m0, s54, 0x2000
	s_nop 0
	global_load_lds_dwordx4 v154, s[30:31]
	s_mov_b32 m0, s88
	s_nop 0
	s_add_u32 s62, s86, 0x80
	s_addc_u32 s63, s87, 0
	global_load_lds_dwordx4 v160, s[62:63]
	s_mov_b32 m0, s46
	s_nop 0
	global_load_lds_dwordx4 v156, s[62:63]
	s_waitcnt vmcnt(8)
	s_waitcnt lgkmcnt(0)
	s_barrier
	s_waitcnt lgkmcnt(0)
	v_mfma_f32_16x16x32_bf16 v[92:95], v[128:131], v[206:209], v[92:95]
	v_mfma_f32_16x16x32_bf16 v[88:91], v[136:139], v[206:209], v[88:91]
	v_mfma_f32_16x16x32_bf16 v[84:87], v[128:131], v[214:217], v[84:87]
	v_mfma_f32_16x16x32_bf16 v[80:83], v[136:139], v[214:217], v[80:83]
	v_mfma_f32_16x16x32_bf16 v[76:79], v[128:131], v[222:225], v[76:79]
	v_mfma_f32_16x16x32_bf16 v[72:75], v[136:139], v[222:225], v[72:75]
	v_mfma_f32_16x16x32_bf16 v[60:63], v[128:131], v[230:233], v[60:63]
	v_mfma_f32_16x16x32_bf16 v[56:59], v[136:139], v[230:233], v[56:59]
	v_mfma_f32_16x16x32_bf16 v[92:95], v[132:135], v[210:213], v[92:95]
	v_mfma_f32_16x16x32_bf16 v[88:91], v[140:143], v[210:213], v[88:91]
	v_mfma_f32_16x16x32_bf16 v[84:87], v[132:135], v[218:221], v[84:87]
	v_mfma_f32_16x16x32_bf16 v[80:83], v[140:143], v[218:221], v[80:83]
	v_mfma_f32_16x16x32_bf16 v[76:79], v[132:135], v[226:229], v[76:79]
	v_mfma_f32_16x16x32_bf16 v[72:75], v[140:143], v[226:229], v[72:75]
	v_mfma_f32_16x16x32_bf16 v[60:63], v[132:135], v[234:237], v[60:63]
	v_mfma_f32_16x16x32_bf16 v[56:59], v[140:143], v[234:237], v[56:59]
	v_mfma_f32_16x16x32_bf16 v[28:31], v[144:147], v[206:209], v[28:31]
	v_mfma_f32_16x16x32_bf16 v[24:27], v[180:183], v[206:209], v[24:27]
	v_mfma_f32_16x16x32_bf16 v[20:23], v[144:147], v[214:217], v[20:23]
	v_mfma_f32_16x16x32_bf16 v[16:19], v[180:183], v[214:217], v[16:19]
	v_mfma_f32_16x16x32_bf16 v[12:15], v[144:147], v[222:225], v[12:15]
	v_mfma_f32_16x16x32_bf16 v[8:11], v[180:183], v[222:225], v[8:11]
	v_mfma_f32_16x16x32_bf16 v[4:7], v[144:147], v[230:233], v[4:7]
	v_mfma_f32_16x16x32_bf16 v[0:3], v[180:183], v[230:233], v[0:3]
	v_mfma_f32_16x16x32_bf16 v[28:31], v[148:151], v[210:213], v[28:31]
	v_mfma_f32_16x16x32_bf16 v[24:27], v[184:187], v[210:213], v[24:27]
	v_mfma_f32_16x16x32_bf16 v[20:23], v[148:151], v[218:221], v[20:23]
	v_mfma_f32_16x16x32_bf16 v[16:19], v[184:187], v[218:221], v[16:19]
	v_mfma_f32_16x16x32_bf16 v[12:15], v[148:151], v[226:229], v[12:15]
	v_mfma_f32_16x16x32_bf16 v[8:11], v[184:187], v[226:229], v[8:11]
	v_mfma_f32_16x16x32_bf16 v[4:7], v[148:151], v[234:237], v[4:7]
	v_mfma_f32_16x16x32_bf16 v[0:3], v[184:187], v[234:237], v[0:3]
	s_barrier
	s_add_i32 s29, s29, 2
	s_add_u32 s82, s82, 0x100
	s_addc_u32 s83, s83, 0
	s_add_u32 vcc_lo, vcc_lo, 0x100
	s_addc_u32 vcc_hi, vcc_hi, 0
	s_cmp_gt_u32 s29, 29
	s_cbranch_scc0 .LBB0_68
	s_and_b64 vcc, exec, s[64:65]
	s_cbranch_vccz .LBB0_71
	s_barrier

; #define PG8_STAGE(bufoff, gbase, voff) do { _Pragma("unroll") for (int _i = 0; _i < 2; ++_i) \
;         __builtin_amdgcn_global_load_lds((const unsigned*)((const char*)(gbase) + (voff)[_i]), (PG8_LAS unsigned*)(lds + (bufoff) + ldsw + _i * 8192), 16, 0, 0); } while (0)
; #define PG8_LDA(dst, b, h) do { _Pragma("unroll") for (int m = 0; m < 4; ++m) _Pragma("unroll") for (int k = 0; k < 2; ++k) dst[m][k] = *(const PG8_LAS bf16x8*)(lds + PG8_SA(b, h) + aoff + m * 2048 + k * 1024); } while (0)
; #define PG8_LDB(dst, b, h) do { _Pragma("unroll") for (int n = 0; n < 2; ++n) _Pragma("unroll") for (int k = 0; k < 2; ++k) dst[n][k] = *(const PG8_LAS bf16x8*)(lds + PG8_SB(b, h) + boff + n * 2048 + k * 1024); } while (0)
; template <class Epi, class Sched, bool ALIGN_EPI = false, bool SP2 = false>
; __device__ __forceinline__ void gemm_phase(PG8_LAS unsigned char* lds, const Gemm g, const Sched& S, const Epi& E) {
;     ...
;         for (int t = 0; t < nt; t += 2) {
;             const bool last = (t == nt - 2);
;             const char* a1 = cA + (size_t)(t + 1) * kstep;
;             const char* a2 = last ? nA : cA + (size_t)(t + 2) * kstep; const char* b2 = last ? nB : cB + (size_t)(t + 2) * kstep;
;             const char* a3 = a2 + kstep; const char* b3 = b2 + kstep;
;             if (last && has_next) S.a_ready(nxt);
;             if constexpr (SP2) {
;             PG8_LDB(B0, 0, 0); PG8_LDB(B1, 0, 1); PG8_SCHED; PG8_LDA(At, 0, 0); PG8_STAGE(PG8_SA(1, 1), a1 + hstep, voffA);
;             PG8_WAIT_V(8); PG8_WAIT_L(0); PG8_BAR; PG8_MMA(0, 0, At, B0); PG8_MMA(0, 1, At, B1); PG8_BAR; PG8_SCHED;
;             PG8_LDA(At, 0, 1); PG8_STAGE(PG8_SB(0, 0), b2, voffB); PG8_STAGE(PG8_SB(0, 1), b2 + hstep, voffB); PG8_STAGE(PG8_SA(0, 0), a2, voffA);
;             PG8_WAIT_V(8); PG8_WAIT_L(0); PG8_BAR; PG8_MMA(1, 0, At, B0); PG8_MMA(1, 1, At, B1); PG8_BAR; PG8_SCHED;
;             PG8_LDB(B0, 1, 0); PG8_LDB(B1, 1, 1); PG8_SCHED; PG8_LDA(At, 1, 0); PG8_STAGE(PG8_SA(0, 1), a2 + hstep, voffA);
;             PG8_WAIT_V(8); PG8_WAIT_L(0); PG8_BAR; PG8_MMA(0, 0, At, B0); PG8_MMA(0, 1, At, B1); PG8_BAR; PG8_SCHED;
;             PG8_LDA(At, 1, 1); PG8_STAGE(PG8_SB(1, 0), b3, voffB); PG8_STAGE(PG8_SB(1, 1), b3 + hstep, voffB); PG8_STAGE(PG8_SA(1, 0), a3, voffA);
;             PG8_WAIT_V(8); PG8_WAIT_L(0); PG8_BAR; PG8_MMA(1, 0, At, B0); PG8_MMA(1, 1, At, B1); PG8_BAR; PG8_SCHED;
.LBB0_283:
	ds_read_b128 v[152:155], v149
	ds_read_b128 v[156:159], v149 offset:1024
	ds_read_b128 v[160:163], v149 offset:2048
	ds_read_b128 v[164:167], v149 offset:3072
	ds_read_b128 v[168:171], v150
	ds_read_b128 v[172:175], v150 offset:1024
	ds_read_b128 v[180:183], v150 offset:2048
	ds_read_b128 v[184:187], v150 offset:3072
	s_add_u32 s30, s66, 0xfff80080
	s_addc_u32 s31, s67, -1
	s_cmp_eq_u32 s85, 28
	s_cselect_b32 s71, s59, s31
	s_cselect_b32 s70, s81, s30
	s_cselect_b32 s69, s57, s84
	s_cselect_b32 s68, s82, s83
	s_add_i32 m0, s29, 0xc000
	ds_read_b128 v[188:191], v151
	ds_read_b128 v[192:195], v151 offset:1024
	ds_read_b128 v[196:199], v151 offset:2048
	ds_read_b128 v[200:203], v151 offset:3072
	ds_read_b128 v[204:207], v151 offset:4096
	ds_read_b128 v[208:211], v151 offset:5120
	ds_read_b128 v[212:215], v151 offset:6144
	ds_read_b128 v[216:219], v151 offset:7168
	global_load_lds_dwordx4 v136, s[66:67]
	s_add_i32 m0, s29, 0xe000
	s_nop 0
	global_load_lds_dwordx4 v138, s[66:67]
	s_waitcnt vmcnt(8)
	s_waitcnt lgkmcnt(0)
	s_barrier
	s_waitcnt lgkmcnt(0)
	v_mfma_f32_16x16x32_bf16 v[124:127], v[152:155], v[188:191], v[124:127]
	v_mfma_f32_16x16x32_bf16 v[120:123], v[160:163], v[188:191], v[120:123]
	v_mfma_f32_16x16x32_bf16 v[116:119], v[152:155], v[196:199], v[116:119]
	v_mfma_f32_16x16x32_bf16 v[108:111], v[160:163], v[196:199], v[108:111]
	v_mfma_f32_16x16x32_bf16 v[100:103], v[152:155], v[204:207], v[100:103]
	v_mfma_f32_16x16x32_bf16 v[92:95], v[160:163], v[204:207], v[92:95]
	v_mfma_f32_16x16x32_bf16 v[84:87], v[152:155], v[212:215], v[84:87]
	v_mfma_f32_16x16x32_bf16 v[76:79], v[160:163], v[212:215], v[76:79]
	v_mfma_f32_16x16x32_bf16 v[124:127], v[156:159], v[192:195], v[124:127]
	v_mfma_f32_16x16x32_bf16 v[120:123], v[164:167], v[192:195], v[120:123]
	v_mfma_f32_16x16x32_bf16 v[116:119], v[156:159], v[200:203], v[116:119]
	v_mfma_f32_16x16x32_bf16 v[108:111], v[164:167], v[200:203], v[108:111]
	v_mfma_f32_16x16x32_bf16 v[100:103], v[156:159], v[208:211], v[100:103]
	v_mfma_f32_16x16x32_bf16 v[92:95], v[164:167], v[208:211], v[92:95]
	v_mfma_f32_16x16x32_bf16 v[84:87], v[156:159], v[216:219], v[84:87]
	v_mfma_f32_16x16x32_bf16 v[76:79], v[164:167], v[216:219], v[76:79]
	v_mfma_f32_16x16x32_bf16 v[112:115], v[168:171], v[188:191], v[112:115]
	v_mfma_f32_16x16x32_bf16 v[104:107], v[180:183], v[188:191], v[104:107]
	v_mfma_f32_16x16x32_bf16 v[96:99], v[168:171], v[196:199], v[96:99]
	v_mfma_f32_16x16x32_bf16 v[88:91], v[180:183], v[196:199], v[88:91]
	v_mfma_f32_16x16x32_bf16 v[80:83], v[168:171], v[204:207], v[80:83]
	v_mfma_f32_16x16x32_bf16 v[72:75], v[180:183], v[204:207], v[72:75]
	v_mfma_f32_16x16x32_bf16 v[68:71], v[168:171], v[212:215], v[68:71]
	v_mfma_f32_16x16x32_bf16 v[64:67], v[180:183], v[212:215], v[64:67]
	v_mfma_f32_16x16x32_bf16 v[112:115], v[172:175], v[192:195], v[112:115]
	v_mfma_f32_16x16x32_bf16 v[104:107], v[184:187], v[192:195], v[104:107]
	v_mfma_f32_16x16x32_bf16 v[96:99], v[172:175], v[200:203], v[96:99]
	v_mfma_f32_16x16x32_bf16 v[88:91], v[184:187], v[200:203], v[88:91]
	v_mfma_f32_16x16x32_bf16 v[80:83], v[172:175], v[208:211], v[80:83]
	v_mfma_f32_16x16x32_bf16 v[72:75], v[184:187], v[208:211], v[72:75]
	v_mfma_f32_16x16x32_bf16 v[68:71], v[172:175], v[216:219], v[68:71]
	v_mfma_f32_16x16x32_bf16 v[64:67], v[184:187], v[216:219], v[64:67]
	s_barrier
	s_add_i32 s30, s74, s1
	s_mov_b32 m0, s30
	ds_read_b128 v[188:191], v151 offset:16384
	ds_read_b128 v[192:195], v151 offset:17408
	ds_read_b128 v[196:199], v151 offset:18432
	ds_read_b128 v[200:203], v151 offset:19456
	ds_read_b128 v[204:207], v151 offset:20480
	ds_read_b128 v[208:211], v151 offset:21504
	ds_read_b128 v[212:215], v151 offset:22528
	ds_read_b128 v[216:219], v151 offset:23552
	global_load_lds_dwordx4 v130, s[68:69]
	s_add_i32 m0, s30, 0x2000
	s_add_u32 s30, s68, 0x80000
	s_addc_u32 s31, s69, 0
	s_add_i32 s86, s75, s1
	global_load_lds_dwordx4 v134, s[68:69]
	s_mov_b32 m0, s86
	s_nop 0
	global_load_lds_dwordx4 v130, s[30:31]
	s_add_i32 m0, s86, 0x2000
	s_nop 0
	global_load_lds_dwordx4 v134, s[30:31]
	s_mov_b32 m0, s29
	s_nop 0
	global_load_lds_dwordx4 v128, s[70:71]
	s_mov_b32 m0, s33
	s_nop 0
	global_load_lds_dwordx4 v132, s[70:71]
	s_waitcnt vmcnt(8)
	s_waitcnt lgkmcnt(0)
	s_barrier
	s_waitcnt lgkmcnt(0)
	v_mfma_f32_16x16x32_bf16 v[60:63], v[152:155], v[188:191], v[60:63]
	v_mfma_f32_16x16x32_bf16 v[56:59], v[160:163], v[188:191], v[56:59]
	v_mfma_f32_16x16x32_bf16 v[52:55], v[152:155], v[196:199], v[52:55]
	v_mfma_f32_16x16x32_bf16 v[44:47], v[160:163], v[196:199], v[44:47]
	v_mfma_f32_16x16x32_bf16 v[36:39], v[152:155], v[204:207], v[36:39]
	v_mfma_f32_16x16x32_bf16 v[28:31], v[160:163], v[204:207], v[28:31]
	v_mfma_f32_16x16x32_bf16 v[20:23], v[152:155], v[212:215], v[20:23]
	v_mfma_f32_16x16x32_bf16 v[12:15], v[160:163], v[212:215], v[12:15]
	v_mfma_f32_16x16x32_bf16 v[60:63], v[156:159], v[192:195], v[60:63]
	v_mfma_f32_16x16x32_bf16 v[56:59], v[164:167], v[192:195], v[56:59]
	v_mfma_f32_16x16x32_bf16 v[52:55], v[156:159], v[200:203], v[52:55]
	v_mfma_f32_16x16x32_bf16 v[44:47], v[164:167], v[200:203], v[44:47]
	v_mfma_f32_16x16x32_bf16 v[36:39], v[156:159], v[208:211], v[36:39]
	v_mfma_f32_16x16x32_bf16 v[28:31], v[164:167], v[208:211], v[28:31]
	v_mfma_f32_16x16x32_bf16 v[20:23], v[156:159], v[216:219], v[20:23]
	v_mfma_f32_16x16x32_bf16 v[12:15], v[164:167], v[216:219], v[12:15]
	v_mfma_f32_16x16x32_bf16 v[48:51], v[168:171], v[188:191], v[48:51]
	v_mfma_f32_16x16x32_bf16 v[40:43], v[180:183], v[188:191], v[40:43]
	v_mfma_f32_16x16x32_bf16 v[32:35], v[168:171], v[196:199], v[32:35]
	v_mfma_f32_16x16x32_bf16 v[24:27], v[180:183], v[196:199], v[24:27]
	v_mfma_f32_16x16x32_bf16 v[16:19], v[168:171], v[204:207], v[16:19]
	v_mfma_f32_16x16x32_bf16 v[8:11], v[180:183], v[204:207], v[8:11]
	v_mfma_f32_16x16x32_bf16 v[4:7], v[168:171], v[212:215], v[4:7]
	v_mfma_f32_16x16x32_bf16 v[0:3], v[180:183], v[212:215], v[0:3]
	v_mfma_f32_16x16x32_bf16 v[48:51], v[172:175], v[192:195], v[48:51]
	v_mfma_f32_16x16x32_bf16 v[40:43], v[184:187], v[192:195], v[40:43]
	v_mfma_f32_16x16x32_bf16 v[32:35], v[172:175], v[200:203], v[32:35]
	v_mfma_f32_16x16x32_bf16 v[24:27], v[184:187], v[200:203], v[24:27]
	v_mfma_f32_16x16x32_bf16 v[16:19], v[172:175], v[208:211], v[16:19]
	v_mfma_f32_16x16x32_bf16 v[8:11], v[184:187], v[208:211], v[8:11]
	v_mfma_f32_16x16x32_bf16 v[4:7], v[172:175], v[216:219], v[4:7]
	v_mfma_f32_16x16x32_bf16 v[0:3], v[184:187], v[216:219], v[0:3]
	s_barrier
; #define PG8_STAGE(bufoff, gbase, voff) do { _Pragma("unroll") for (int _i = 0; _i < 2; ++_i) \
;         __builtin_amdgcn_global_load_lds((const unsigned*)((const char*)(gbase) + (voff)[_i]), (PG8_LAS unsigned*)(lds + (bufoff) + ldsw + _i * 8192), 16, 0, 0); } while (0)
; #define PG8_LDA(dst, b, h) do { _Pragma("unroll") for (int m = 0; m < 4; ++m) _Pragma("unroll") for (int k = 0; k < 2; ++k) dst[m][k] = *(const PG8_LAS bf16x8*)(lds + PG8_SA(b, h) + aoff + m * 2048 + k * 1024); } while (0)
; #define PG8_LDB(dst, b, h) do { _Pragma("unroll") for (int n = 0; n < 2; ++n) _Pragma("unroll") for (int k = 0; k < 2; ++k) dst[n][k] = *(const PG8_LAS bf16x8*)(lds + PG8_SB(b, h) + boff + n * 2048 + k * 1024); } while (0)
; template <class Epi, class Sched, bool ALIGN_EPI = false, bool SP2 = false>
; __device__ __forceinline__ void gemm_phase(PG8_LAS unsigned char* lds, const Gemm g, const Sched& S, const Epi& E) {
;     ...
;         for (int t = 0; t < nt; t += 2) {
;             const bool last = (t == nt - 2);
;             const char* a1 = cA + (size_t)(t + 1) * kstep;
;             const char* a2 = last ? nA : cA + (size_t)(t + 2) * kstep; const char* b2 = last ? nB : cB + (size_t)(t + 2) * kstep;
;             const char* a3 = a2 + kstep; const char* b3 = b2 + kstep;
;             if (last && has_next) S.a_ready(nxt);
;             if constexpr (SP2) {
;             PG8_LDB(B0, 0, 0); PG8_LDB(B1, 0, 1); PG8_SCHED; PG8_LDA(At, 0, 0); PG8_STAGE(PG8_SA(1, 1), a1 + hstep, voffA);
;             PG8_WAIT_V(8); PG8_WAIT_L(0); PG8_BAR; PG8_MMA(0, 0, At, B0); PG8_MMA(0, 1, At, B1); PG8_BAR; PG8_SCHED;
;             PG8_LDA(At, 0, 1); PG8_STAGE(PG8_SB(0, 0), b2, voffB); PG8_STAGE(PG8_SB(0, 1), b2 + hstep, voffB); PG8_STAGE(PG8_SA(0, 0), a2, voffA);
;             PG8_WAIT_V(8); PG8_WAIT_L(0); PG8_BAR; PG8_MMA(1, 0, At, B0); PG8_MMA(1, 1, At, B1); PG8_BAR; PG8_SCHED;
;             PG8_LDB(B0, 1, 0); PG8_LDB(B1, 1, 1); PG8_SCHED; PG8_LDA(At, 1, 0); PG8_STAGE(PG8_SA(0, 1), a2 + hstep, voffA);
;             PG8_WAIT_V(8); PG8_WAIT_L(0); PG8_BAR; PG8_MMA(0, 0, At, B0); PG8_MMA(0, 1, At, B1); PG8_BAR; PG8_SCHED;
;             PG8_LDA(At, 1, 1); PG8_STAGE(PG8_SB(1, 0), b3, voffB); PG8_STAGE(PG8_SB(1, 1), b3 + hstep, voffB); PG8_STAGE(PG8_SA(1, 0), a3, voffA);
;             PG8_WAIT_V(8); PG8_WAIT_L(0); PG8_BAR; PG8_MMA(1, 0, At, B0); PG8_MMA(1, 1, At, B1); PG8_BAR; PG8_SCHED;
	s_add_i32 s86, 0, 0x18000
	s_add_i32 s87, 0, 0x1c000
	v_add_u32_e32 v164, s86, v147
	v_add_u32_e32 v179, s87, v147
	ds_read_b128 v[152:155], v164
	ds_read_b128 v[156:159], v164 offset:1024
	ds_read_b128 v[160:163], v164 offset:2048
	ds_read_b128 v[164:167], v164 offset:3072
	ds_read_b128 v[168:171], v179
	ds_read_b128 v[172:175], v179 offset:1024
	ds_read_b128 v[180:183], v179 offset:2048
	ds_read_b128 v[184:187], v179 offset:3072
	s_add_u32 s30, s70, 0x80000
	s_addc_u32 s31, s71, 0
	s_mov_b32 m0, s46
	ds_read_b128 v[188:191], v151 offset:32768
	ds_read_b128 v[192:195], v151 offset:33792
	ds_read_b128 v[196:199], v151 offset:34816
	ds_read_b128 v[200:203], v151 offset:35840
	ds_read_b128 v[204:207], v151 offset:36864
	ds_read_b128 v[208:211], v151 offset:37888
	ds_read_b128 v[212:215], v151 offset:38912
	ds_read_b128 v[216:219], v151 offset:39936
	global_load_lds_dwordx4 v128, s[30:31]
	s_mov_b32 m0, s47
	s_nop 0
	global_load_lds_dwordx4 v132, s[30:31]
	s_waitcnt vmcnt(8)
	s_waitcnt lgkmcnt(0)
	s_barrier
	s_waitcnt lgkmcnt(0)
	v_mfma_f32_16x16x32_bf16 v[124:127], v[152:155], v[188:191], v[124:127]
	v_mfma_f32_16x16x32_bf16 v[120:123], v[160:163], v[188:191], v[120:123]
	v_mfma_f32_16x16x32_bf16 v[116:119], v[152:155], v[196:199], v[116:119]
	v_mfma_f32_16x16x32_bf16 v[108:111], v[160:163], v[196:199], v[108:111]
	v_mfma_f32_16x16x32_bf16 v[100:103], v[152:155], v[204:207], v[100:103]
	v_mfma_f32_16x16x32_bf16 v[92:95], v[160:163], v[204:207], v[92:95]
	v_mfma_f32_16x16x32_bf16 v[84:87], v[152:155], v[212:215], v[84:87]
	v_mfma_f32_16x16x32_bf16 v[76:79], v[160:163], v[212:215], v[76:79]
	v_mfma_f32_16x16x32_bf16 v[124:127], v[156:159], v[192:195], v[124:127]
	v_mfma_f32_16x16x32_bf16 v[120:123], v[164:167], v[192:195], v[120:123]
	v_mfma_f32_16x16x32_bf16 v[116:119], v[156:159], v[200:203], v[116:119]
	v_mfma_f32_16x16x32_bf16 v[108:111], v[164:167], v[200:203], v[108:111]
	v_mfma_f32_16x16x32_bf16 v[100:103], v[156:159], v[208:211], v[100:103]
	v_mfma_f32_16x16x32_bf16 v[92:95], v[164:167], v[208:211], v[92:95]
	v_mfma_f32_16x16x32_bf16 v[84:87], v[156:159], v[216:219], v[84:87]
	v_mfma_f32_16x16x32_bf16 v[76:79], v[164:167], v[216:219], v[76:79]
	v_mfma_f32_16x16x32_bf16 v[112:115], v[168:171], v[188:191], v[112:115]
	v_mfma_f32_16x16x32_bf16 v[104:107], v[180:183], v[188:191], v[104:107]
	v_mfma_f32_16x16x32_bf16 v[96:99], v[168:171], v[196:199], v[96:99]
	v_mfma_f32_16x16x32_bf16 v[88:91], v[180:183], v[196:199], v[88:91]
	v_mfma_f32_16x16x32_bf16 v[80:83], v[168:171], v[204:207], v[80:83]
	v_mfma_f32_16x16x32_bf16 v[72:75], v[180:183], v[204:207], v[72:75]
	v_mfma_f32_16x16x32_bf16 v[68:71], v[168:171], v[212:215], v[68:71]
	v_mfma_f32_16x16x32_bf16 v[64:67], v[180:183], v[212:215], v[64:67]
	v_mfma_f32_16x16x32_bf16 v[112:115], v[172:175], v[192:195], v[112:115]
	v_mfma_f32_16x16x32_bf16 v[104:107], v[184:187], v[192:195], v[104:107]
	v_mfma_f32_16x16x32_bf16 v[96:99], v[172:175], v[200:203], v[96:99]
	v_mfma_f32_16x16x32_bf16 v[88:91], v[184:187], v[200:203], v[88:91]
	v_mfma_f32_16x16x32_bf16 v[80:83], v[172:175], v[208:211], v[80:83]
	v_mfma_f32_16x16x32_bf16 v[72:75], v[184:187], v[208:211], v[72:75]
	v_mfma_f32_16x16x32_bf16 v[68:71], v[172:175], v[216:219], v[68:71]
	v_mfma_f32_16x16x32_bf16 v[64:67], v[184:187], v[216:219], v[64:67]
	s_barrier
	s_add_i32 s30, s86, s1
	s_mov_b32 m0, s30
	ds_read_b128 v[188:191], v151 offset:49152
	ds_read_b128 v[192:195], v151 offset:50176
	ds_read_b128 v[196:199], v151 offset:51200
	ds_read_b128 v[200:203], v151 offset:52224
	ds_read_b128 v[204:207], v151 offset:53248
	ds_read_b128 v[208:211], v151 offset:54272
	ds_read_b128 v[212:215], v151 offset:55296
	ds_read_b128 v[216:219], v151 offset:56320
	s_add_u32 s8, s68, 0x80
	s_addc_u32 s9, s69, 0
	global_load_lds_dwordx4 v130, s[8:9]
	s_add_i32 m0, s30, 0x2000
	s_add_u32 s30, s68, 0x80080
	s_addc_u32 s31, s69, 0
	s_add_i32 s68, s87, s1
	global_load_lds_dwordx4 v134, s[8:9]
	s_mov_b32 m0, s68
	s_nop 0
	global_load_lds_dwordx4 v130, s[30:31]
	s_add_i32 m0, s68, 0x2000
	s_nop 0
	global_load_lds_dwordx4 v134, s[30:31]
	s_mov_b32 m0, s72
	s_nop 0
	s_add_u32 s8, s70, 0x80
	s_addc_u32 s9, s71, 0
	global_load_lds_dwordx4 v128, s[8:9]
	s_mov_b32 m0, s73
	s_nop 0
	global_load_lds_dwordx4 v132, s[8:9]
	s_waitcnt vmcnt(8)
	s_waitcnt lgkmcnt(0)
	s_barrier
	s_waitcnt lgkmcnt(0)
	v_mfma_f32_16x16x32_bf16 v[60:63], v[152:155], v[188:191], v[60:63]
	v_mfma_f32_16x16x32_bf16 v[56:59], v[160:163], v[188:191], v[56:59]
	v_mfma_f32_16x16x32_bf16 v[52:55], v[152:155], v[196:199], v[52:55]
	v_mfma_f32_16x16x32_bf16 v[44:47], v[160:163], v[196:199], v[44:47]
	v_mfma_f32_16x16x32_bf16 v[36:39], v[152:155], v[204:207], v[36:39]
	v_mfma_f32_16x16x32_bf16 v[28:31], v[160:163], v[204:207], v[28:31]
	v_mfma_f32_16x16x32_bf16 v[20:23], v[152:155], v[212:215], v[20:23]
	v_mfma_f32_16x16x32_bf16 v[12:15], v[160:163], v[212:215], v[12:15]
	v_mfma_f32_16x16x32_bf16 v[60:63], v[156:159], v[192:195], v[60:63]
	v_mfma_f32_16x16x32_bf16 v[56:59], v[164:167], v[192:195], v[56:59]
	v_mfma_f32_16x16x32_bf16 v[52:55], v[156:159], v[200:203], v[52:55]
	v_mfma_f32_16x16x32_bf16 v[44:47], v[164:167], v[200:203], v[44:47]
	v_mfma_f32_16x16x32_bf16 v[36:39], v[156:159], v[208:211], v[36:39]
	v_mfma_f32_16x16x32_bf16 v[28:31], v[164:167], v[208:211], v[28:31]
	v_mfma_f32_16x16x32_bf16 v[20:23], v[156:159], v[216:219], v[20:23]
	v_mfma_f32_16x16x32_bf16 v[12:15], v[164:167], v[216:219], v[12:15]
	v_mfma_f32_16x16x32_bf16 v[48:51], v[168:171], v[188:191], v[48:51]
	v_mfma_f32_16x16x32_bf16 v[40:43], v[180:183], v[188:191], v[40:43]
	v_mfma_f32_16x16x32_bf16 v[32:35], v[168:171], v[196:199], v[32:35]
	v_mfma_f32_16x16x32_bf16 v[24:27], v[180:183], v[196:199], v[24:27]
	v_mfma_f32_16x16x32_bf16 v[16:19], v[168:171], v[204:207], v[16:19]
	v_mfma_f32_16x16x32_bf16 v[8:11], v[180:183], v[204:207], v[8:11]
	v_mfma_f32_16x16x32_bf16 v[4:7], v[168:171], v[212:215], v[4:7]
	v_mfma_f32_16x16x32_bf16 v[0:3], v[180:183], v[212:215], v[0:3]
	v_mfma_f32_16x16x32_bf16 v[48:51], v[172:175], v[192:195], v[48:51]
	v_mfma_f32_16x16x32_bf16 v[40:43], v[184:187], v[192:195], v[40:43]
	v_mfma_f32_16x16x32_bf16 v[32:35], v[172:175], v[200:203], v[32:35]
	v_mfma_f32_16x16x32_bf16 v[24:27], v[184:187], v[200:203], v[24:27]
	v_mfma_f32_16x16x32_bf16 v[16:19], v[172:175], v[208:211], v[16:19]
	v_mfma_f32_16x16x32_bf16 v[8:11], v[184:187], v[208:211], v[8:11]
	v_mfma_f32_16x16x32_bf16 v[4:7], v[172:175], v[216:219], v[4:7]
	v_mfma_f32_16x16x32_bf16 v[0:3], v[184:187], v[216:219], v[0:3]
	s_barrier
; __device__ __forceinline__ unsigned cvt_pk_bf16(float lo, float hi) { unsigned r; asm volatile("v_cvt_pk_bf16_f32 %0, %1, %2" : "=v"(r) : "v"(lo), "v"(hi)); return r; }
; #define PG8_WAIT_V(n) asm volatile("s_waitcnt vmcnt(" #n ")" ::: "memory")
; #define PG8_BAR __builtin_amdgcn_s_barrier()
;     __device__ __forceinline__ void operator()(const f32x4 (&acc)[2][2][4][2], const Unit& u, int wr, int wc, int fr, int fq) const {
;         const int row0 = u.pm * BM + wr * 64 + fr; const int col0 = u.pn * BM + wc * 32 + 8 * fq;
; #pragma unroll
;         for (int ai = 0; ai < 2; ++ai)
; #pragma unroll
;             for (int m = 0; m < 4; ++m) { bf16_t* rowp = O + (size_t)(row0 + ai * HALF + m * 16) * ldc + col0;
; #pragma unroll
;                 for (int bj = 0; bj < 2; ++bj) { const f32x4 v0 = acc[ai][bj][m][0], v1 = acc[ai][bj][m][1];
;                     u32x4 w; w.x = cvt_pk_bf16(v0[0], v0[1]); w.y = cvt_pk_bf16(v0[2], v0[3]); w.z = cvt_pk_bf16(v1[0], v1[1]); w.w = cvt_pk_bf16(v1[2], v1[3]);
;                     *(u32x4*)(rowp + bj * HALF) = w; } }
;     }
; template <class Epi, class Sched, bool ALIGN_EPI = false, bool SP2 = false>
; __device__ __forceinline__ void gemm_phase(PG8_LAS unsigned char* lds, const Gemm g, const Sched& S, const Epi& E) {
;     ...
;         if constexpr (!Epi::AFTER_DRAIN) { E(acc, cur, wr, wc, fr, fq); S.done(cur); }
;         if (!has_next) break;
; #pragma unroll
;         for (int a = 0; a < 2; ++a)
; #pragma unroll
;             for (int b = 0; b < 2; ++b)
; #pragma unroll
;                 for (int m = 0; m < 4; ++m)
; #pragma unroll
;                     for (int n = 0; n < 2; ++n) acc[a][b][m][n] = (f32x4){0.f, 0.f, 0.f, 0.f};
;         cur = nxt; cA = nA; cB = nB; ++ui;
;         if constexpr (ALIGN_EPI) { if (wr == 1) PG8_BAR; }
;     }
;     PG8_WAIT_V(0);
;     if constexpr (!ALIGN_EPI) { if (wr == 0) PG8_BAR; }
	s_add_i32 s85, s85, 2
	s_add_u32 s66, s66, 0x100
	s_addc_u32 s67, s67, 0
	s_add_u32 s83, s83, 0x100
	s_addc_u32 s84, s84, 0
	s_cmp_gt_u32 s85, 29
	s_cbranch_scc0 .LBB0_283
	v_lshl_add_u32 v152, s64, 8, v146
	v_lshl_or_b32 v144, s80, 8, v148
	v_ashrrev_i32_e32 v153, 31, v152
	v_ashrrev_i32_e32 v145, 31, v144
	v_lshlrev_b64 v[154:155], 12, v[152:153]
	v_lshl_add_u64 v[154:155], s[18:19], 0, v[154:155]
	v_lshlrev_b64 v[156:157], 1, v[144:145]
	v_lshl_add_u64 v[144:145], v[154:155], 0, v[156:157]
	v_cvt_pk_bf16_f32 v124, v124, v125
	v_cvt_pk_bf16_f32 v125, v126, v127
	v_cvt_pk_bf16_f32 v126, v120, v121
	v_cvt_pk_bf16_f32 v127, v122, v123
	global_store_dwordx4 v[144:145], v[124:127], off
	v_cvt_pk_bf16_f32 v112, v112, v113
	v_cvt_pk_bf16_f32 v113, v114, v115
	v_cvt_pk_bf16_f32 v114, v104, v105
	v_or_b32_e32 v104, 16, v152
	v_ashrrev_i32_e32 v105, 31, v104
	v_lshlrev_b64 v[104:105], 12, v[104:105]
	v_lshl_add_u64 v[104:105], s[18:19], 0, v[104:105]
	v_cvt_pk_bf16_f32 v115, v106, v107
	global_store_dwordx4 v[144:145], v[112:115], off offset:256
	s_mov_b32 s80, s56
	s_mov_b32 s64, s58
	v_lshl_add_u64 v[112:113], v[104:105], 0, v[156:157]
	v_cvt_pk_bf16_f32 v104, v116, v117
	v_cvt_pk_bf16_f32 v105, v118, v119
	v_cvt_pk_bf16_f32 v106, v108, v109
	v_cvt_pk_bf16_f32 v107, v110, v111
	global_store_dwordx4 v[112:113], v[104:107], off
	v_cvt_pk_bf16_f32 v96, v96, v97
	v_cvt_pk_bf16_f32 v97, v98, v99
	v_cvt_pk_bf16_f32 v98, v88, v89
	v_or_b32_e32 v88, 32, v152
	v_ashrrev_i32_e32 v89, 31, v88
	v_lshlrev_b64 v[88:89], 12, v[88:89]
	v_lshl_add_u64 v[88:89], s[18:19], 0, v[88:89]
	v_cvt_pk_bf16_f32 v99, v90, v91
	global_store_dwordx4 v[112:113], v[96:99], off offset:256
	s_mov_b64 s[68:69], s[62:63]
	s_mov_b64 s[66:67], s[60:61]
	v_lshl_add_u64 v[96:97], v[88:89], 0, v[156:157]
	v_cvt_pk_bf16_f32 v88, v100, v101
	v_cvt_pk_bf16_f32 v89, v102, v103
	v_cvt_pk_bf16_f32 v90, v92, v93
	v_cvt_pk_bf16_f32 v91, v94, v95
	global_store_dwordx4 v[96:97], v[88:91], off
	v_cvt_pk_bf16_f32 v80, v80, v81
	v_cvt_pk_bf16_f32 v81, v82, v83
	v_cvt_pk_bf16_f32 v82, v72, v73
	v_or_b32_e32 v72, 48, v152
	v_ashrrev_i32_e32 v73, 31, v72
	v_lshlrev_b64 v[72:73], 12, v[72:73]
	v_lshl_add_u64 v[72:73], s[18:19], 0, v[72:73]
	v_cvt_pk_bf16_f32 v83, v74, v75
	global_store_dwordx4 v[96:97], v[80:83], off offset:256
	s_nop 1
	v_lshl_add_u64 v[80:81], v[72:73], 0, v[156:157]
	v_cvt_pk_bf16_f32 v72, v84, v85
	v_cvt_pk_bf16_f32 v73, v86, v87
	v_cvt_pk_bf16_f32 v74, v76, v77
	v_cvt_pk_bf16_f32 v75, v78, v79
	global_store_dwordx4 v[80:81], v[72:75], off
	v_cvt_pk_bf16_f32 v68, v68, v69
	v_cvt_pk_bf16_f32 v69, v70, v71
	v_cvt_pk_bf16_f32 v70, v64, v65
	v_cvt_pk_bf16_f32 v71, v66, v67
	global_store_dwordx4 v[80:81], v[68:71], off offset:256
	v_cvt_pk_bf16_f32 v60, v60, v61
	v_cvt_pk_bf16_f32 v61, v62, v63
	v_cvt_pk_bf16_f32 v62, v56, v57
	v_add_co_u32_e32 v56, vcc, s76, v144
	v_lshl_add_u64 v[64:65], v[144:145], 0, s[6:7]
	s_nop 0
	v_addc_co_u32_e32 v57, vcc, 0, v145, vcc
	v_cvt_pk_bf16_f32 v63, v58, v59
	global_store_dwordx4 v[56:57], v[60:63], off
	v_cvt_pk_bf16_f32 v48, v48, v49
	v_cvt_pk_bf16_f32 v49, v50, v51
	v_cvt_pk_bf16_f32 v50, v40, v41
	v_cvt_pk_bf16_f32 v51, v42, v43
	global_store_dwordx4 v[64:65], v[48:51], off offset:256
	v_cvt_pk_bf16_f32 v40, v52, v53
	v_cvt_pk_bf16_f32 v41, v54, v55
	v_cvt_pk_bf16_f32 v42, v44, v45
	v_add_co_u32_e32 v44, vcc, s77, v144
	s_nop 0
	v_lshl_add_u64 v[48:49], v[144:145], 0, s[10:11]
	v_addc_co_u32_e32 v45, vcc, 0, v145, vcc
	v_cvt_pk_bf16_f32 v43, v46, v47
	global_store_dwordx4 v[44:45], v[40:43], off
	v_cvt_pk_bf16_f32 v32, v32, v33
	v_cvt_pk_bf16_f32 v33, v34, v35
	v_cvt_pk_bf16_f32 v34, v24, v25
	v_cvt_pk_bf16_f32 v35, v26, v27
	global_store_dwordx4 v[48:49], v[32:35], off offset:256
	v_cvt_pk_bf16_f32 v24, v36, v37
	v_cvt_pk_bf16_f32 v25, v38, v39
	v_cvt_pk_bf16_f32 v26, v28, v29
	v_add_co_u32_e32 v28, vcc, s78, v144
	s_nop 0
	v_lshl_add_u64 v[32:33], v[144:145], 0, s[36:37]
	v_addc_co_u32_e32 v29, vcc, 0, v145, vcc
	v_cvt_pk_bf16_f32 v27, v30, v31
	global_store_dwordx4 v[28:29], v[24:27], off
	v_cvt_pk_bf16_f32 v16, v16, v17
	v_cvt_pk_bf16_f32 v17, v18, v19
	v_cvt_pk_bf16_f32 v18, v8, v9
	v_cvt_pk_bf16_f32 v19, v10, v11
	global_store_dwordx4 v[32:33], v[16:19], off offset:256
	v_cvt_pk_bf16_f32 v8, v20, v21
	v_cvt_pk_bf16_f32 v9, v22, v23
	v_cvt_pk_bf16_f32 v10, v12, v13
	v_add_co_u32_e32 v12, vcc, s79, v144
	s_nop 0
	v_lshl_add_u64 v[16:17], v[144:145], 0, s[54:55]
	v_addc_co_u32_e32 v13, vcc, 0, v145, vcc
	s_and_b64 vcc, exec, s[4:5]
	v_cvt_pk_bf16_f32 v11, v14, v15
	global_store_dwordx4 v[12:13], v[8:11], off
	v_cvt_pk_bf16_f32 v4, v4, v5
	v_cvt_pk_bf16_f32 v5, v6, v7
	v_cvt_pk_bf16_f32 v6, v0, v1
	v_cvt_pk_bf16_f32 v7, v2, v3
	global_store_dwordx4 v[16:17], v[4:7], off offset:256
	s_cbranch_vccz .LBB0_276
	s_waitcnt vmcnt(0)
	s_cmpk_gt_u32 s0, 0xff
	s_cbranch_scc1 .LBB0_287
	s_barrier

; #define PG8_STAGE(bufoff, gbase, voff) do { _Pragma("unroll") for (int _i = 0; _i < 2; ++_i) \
;         __builtin_amdgcn_global_load_lds((const unsigned*)((const char*)(gbase) + (voff)[_i]), (PG8_LAS unsigned*)(lds + (bufoff) + ldsw + _i * 8192), 16, 0, 0); } while (0)
; #define PG8_LDA(dst, b, h) do { _Pragma("unroll") for (int m = 0; m < 4; ++m) _Pragma("unroll") for (int k = 0; k < 2; ++k) dst[m][k] = *(const PG8_LAS bf16x8*)(lds + PG8_SA(b, h) + aoff + m * 2048 + k * 1024); } while (0)
; #define PG8_LDB(dst, b, h) do { _Pragma("unroll") for (int n = 0; n < 2; ++n) _Pragma("unroll") for (int k = 0; k < 2; ++k) dst[n][k] = *(const PG8_LAS bf16x8*)(lds + PG8_SB(b, h) + boff + n * 2048 + k * 1024); } while (0)
; template <class Epi, class Sched, bool ALIGN_EPI = false, bool SP2 = false>
; __device__ __forceinline__ void gemm_phase(PG8_LAS unsigned char* lds, const Gemm g, const Sched& S, const Epi& E) {
;     ...
;         for (int t = 0; t < nt; t += 2) {
;             const bool last = (t == nt - 2);
;             const char* a1 = cA + (size_t)(t + 1) * kstep;
;             const char* a2 = last ? nA : cA + (size_t)(t + 2) * kstep; const char* b2 = last ? nB : cB + (size_t)(t + 2) * kstep;
;             const char* a3 = a2 + kstep; const char* b3 = b2 + kstep;
;             if (last && has_next) S.a_ready(nxt);
;             if constexpr (SP2) {
;             PG8_LDB(B0, 0, 0); PG8_LDB(B1, 0, 1); PG8_SCHED; PG8_LDA(At, 0, 0); PG8_STAGE(PG8_SA(1, 1), a1 + hstep, voffA);
;             PG8_WAIT_V(8); PG8_WAIT_L(0); PG8_BAR; PG8_MMA(0, 0, At, B0); PG8_MMA(0, 1, At, B1); PG8_BAR; PG8_SCHED;
;             PG8_LDA(At, 0, 1); PG8_STAGE(PG8_SB(0, 0), b2, voffB); PG8_STAGE(PG8_SB(0, 1), b2 + hstep, voffB); PG8_STAGE(PG8_SA(0, 0), a2, voffA);
;             PG8_WAIT_V(8); PG8_WAIT_L(0); PG8_BAR; PG8_MMA(1, 0, At, B0); PG8_MMA(1, 1, At, B1); PG8_BAR; PG8_SCHED;
;             PG8_LDB(B0, 1, 0); PG8_LDB(B1, 1, 1); PG8_SCHED; PG8_LDA(At, 1, 0); PG8_STAGE(PG8_SA(0, 1), a2 + hstep, voffA);
;             PG8_WAIT_V(8); PG8_WAIT_L(0); PG8_BAR; PG8_MMA(0, 0, At, B0); PG8_MMA(0, 1, At, B1); PG8_BAR; PG8_SCHED;
;             PG8_LDA(At, 1, 1); PG8_STAGE(PG8_SB(1, 0), b3, voffB); PG8_STAGE(PG8_SB(1, 1), b3 + hstep, voffB); PG8_STAGE(PG8_SA(1, 0), a3, voffA);
;             PG8_WAIT_V(8); PG8_WAIT_L(0); PG8_BAR; PG8_MMA(1, 0, At, B0); PG8_MMA(1, 1, At, B1); PG8_BAR; PG8_SCHED;
.LBB0_404:
	ds_read_b128 v[118:121], v217
	ds_read_b128 v[126:129], v217 offset:1024
	ds_read_b128 v[130:133], v217 offset:2048
	ds_read_b128 v[134:137], v217 offset:3072
	ds_read_b128 v[138:141], v218
	ds_read_b128 v[142:145], v218 offset:1024
	ds_read_b128 v[146:149], v218 offset:2048
	ds_read_b128 v[150:153], v218 offset:3072
	s_add_u32 s30, s10, 0xfff80080
	s_addc_u32 s31, s11, -1
	s_cmp_eq_u32 s65, 28
	s_cselect_b32 s75, s1, s31
	s_cselect_b32 s74, s22, s30
	s_cselect_b32 s73, s33, s63
	s_cselect_b32 s72, s46, s47
	s_add_i32 m0, s77, 0xc000
	ds_read_b128 v[154:157], v219
	ds_read_b128 v[166:169], v219 offset:1024
	ds_read_b128 v[170:173], v219 offset:2048
	ds_read_b128 v[174:177], v219 offset:3072
	ds_read_b128 v[204:207], v219 offset:4096
	ds_read_b128 v[208:211], v219 offset:5120
	ds_read_b128 v[226:229], v219 offset:6144
	ds_read_b128 v[230:233], v219 offset:7168
	global_load_lds_dwordx4 v196, s[10:11]
	s_add_i32 m0, s77, 0xe000
	s_nop 0
	global_load_lds_dwordx4 v198, s[10:11]
	s_waitcnt vmcnt(8)
	s_waitcnt lgkmcnt(0)
	s_barrier
	s_waitcnt lgkmcnt(0)
	v_mfma_f32_16x16x32_bf16 v[162:165], v[118:121], v[154:157], v[162:165]
	v_mfma_f32_16x16x32_bf16 v[60:63], v[130:133], v[154:157], v[60:63]
	v_mfma_f32_16x16x32_bf16 v[122:125], v[118:121], v[170:173], v[122:125]
	v_mfma_f32_16x16x32_bf16 v[52:55], v[130:133], v[170:173], v[52:55]
	v_mfma_f32_16x16x32_bf16 v[108:111], v[118:121], v[204:207], v[108:111]
	v_mfma_f32_16x16x32_bf16 v[44:47], v[130:133], v[204:207], v[44:47]
	v_mfma_f32_16x16x32_bf16 v[104:107], v[118:121], v[226:229], v[104:107]
	v_mfma_f32_16x16x32_bf16 v[40:43], v[130:133], v[226:229], v[40:43]
	v_mfma_f32_16x16x32_bf16 v[162:165], v[126:129], v[166:169], v[162:165]
	v_mfma_f32_16x16x32_bf16 v[60:63], v[134:137], v[166:169], v[60:63]
	v_mfma_f32_16x16x32_bf16 v[122:125], v[126:129], v[174:177], v[122:125]
	v_mfma_f32_16x16x32_bf16 v[52:55], v[134:137], v[174:177], v[52:55]
	v_mfma_f32_16x16x32_bf16 v[108:111], v[126:129], v[208:211], v[108:111]
	v_mfma_f32_16x16x32_bf16 v[44:47], v[134:137], v[208:211], v[44:47]
	v_mfma_f32_16x16x32_bf16 v[104:107], v[126:129], v[230:233], v[104:107]
	v_mfma_f32_16x16x32_bf16 v[40:43], v[134:137], v[230:233], v[40:43]
	v_mfma_f32_16x16x32_bf16 v[158:161], v[138:141], v[154:157], v[158:161]
	v_mfma_f32_16x16x32_bf16 v[56:59], v[146:149], v[154:157], v[56:59]
	v_mfma_f32_16x16x32_bf16 v[112:115], v[138:141], v[170:173], v[114:117]
	v_mfma_f32_16x16x32_bf16 v[48:51], v[146:149], v[170:173], v[48:51]
	v_mfma_f32_16x16x32_bf16 v[100:103], v[138:141], v[204:207], v[100:103]
	v_mfma_f32_16x16x32_bf16 v[36:39], v[146:149], v[204:207], v[36:39]
	v_mfma_f32_16x16x32_bf16 v[96:99], v[138:141], v[226:229], v[96:99]
	v_mfma_f32_16x16x32_bf16 v[32:35], v[146:149], v[226:229], v[32:35]
	v_mfma_f32_16x16x32_bf16 v[158:161], v[142:145], v[166:169], v[158:161]
	v_mfma_f32_16x16x32_bf16 v[56:59], v[150:153], v[166:169], v[56:59]
	v_mfma_f32_16x16x32_bf16 v[112:115], v[142:145], v[174:177], v[112:115]
	v_mfma_f32_16x16x32_bf16 v[48:51], v[150:153], v[174:177], v[48:51]
	v_mfma_f32_16x16x32_bf16 v[100:103], v[142:145], v[208:211], v[100:103]
	v_mfma_f32_16x16x32_bf16 v[36:39], v[150:153], v[208:211], v[36:39]
	v_mfma_f32_16x16x32_bf16 v[96:99], v[142:145], v[230:233], v[96:99]
	v_mfma_f32_16x16x32_bf16 v[32:35], v[150:153], v[230:233], v[32:35]
	s_barrier
	s_add_i32 s30, s85, s29
	s_mov_b32 m0, s30
	ds_read_b128 v[154:157], v219 offset:16384
	ds_read_b128 v[166:169], v219 offset:17408
	ds_read_b128 v[170:173], v219 offset:18432
	ds_read_b128 v[174:177], v219 offset:19456
	ds_read_b128 v[204:207], v219 offset:20480
	ds_read_b128 v[208:211], v219 offset:21504
	ds_read_b128 v[226:229], v219 offset:22528
	ds_read_b128 v[230:233], v219 offset:23552
	global_load_lds_dwordx4 v184, s[72:73]
	s_add_i32 m0, s30, 0x2000
	s_add_u32 s30, s72, 0x80000
	s_addc_u32 s31, s73, 0
	s_add_i32 s71, s86, s29
	global_load_lds_dwordx4 v180, s[72:73]
	s_mov_b32 m0, s71
	s_nop 0
	global_load_lds_dwordx4 v184, s[30:31]
	s_add_i32 m0, s71, 0x2000
	s_nop 0
	global_load_lds_dwordx4 v180, s[30:31]
	s_mov_b32 m0, s77
	s_nop 0
	global_load_lds_dwordx4 v186, s[74:75]
	s_mov_b32 m0, s78
	s_nop 0
	global_load_lds_dwordx4 v182, s[74:75]
	s_waitcnt vmcnt(8)
	s_waitcnt lgkmcnt(0)
	s_barrier
	s_waitcnt lgkmcnt(0)
	v_mfma_f32_16x16x32_bf16 v[92:95], v[118:121], v[154:157], v[92:95]
	v_mfma_f32_16x16x32_bf16 v[28:31], v[130:133], v[154:157], v[28:31]
	v_mfma_f32_16x16x32_bf16 v[84:87], v[118:121], v[170:173], v[84:87]
	v_mfma_f32_16x16x32_bf16 v[20:23], v[130:133], v[170:173], v[20:23]
	v_mfma_f32_16x16x32_bf16 v[76:79], v[118:121], v[204:207], v[76:79]
	v_mfma_f32_16x16x32_bf16 v[12:15], v[130:133], v[204:207], v[12:15]
	v_mfma_f32_16x16x32_bf16 v[72:75], v[118:121], v[226:229], v[72:75]
	v_mfma_f32_16x16x32_bf16 v[8:11], v[130:133], v[226:229], v[8:11]
	v_mfma_f32_16x16x32_bf16 v[92:95], v[126:129], v[166:169], v[92:95]
	v_mfma_f32_16x16x32_bf16 v[28:31], v[134:137], v[166:169], v[28:31]
	v_mfma_f32_16x16x32_bf16 v[84:87], v[126:129], v[174:177], v[84:87]
	v_mfma_f32_16x16x32_bf16 v[20:23], v[134:137], v[174:177], v[20:23]
	v_mfma_f32_16x16x32_bf16 v[76:79], v[126:129], v[208:211], v[76:79]
	v_mfma_f32_16x16x32_bf16 v[12:15], v[134:137], v[208:211], v[12:15]
	v_mfma_f32_16x16x32_bf16 v[72:75], v[126:129], v[230:233], v[72:75]
	v_mfma_f32_16x16x32_bf16 v[8:11], v[134:137], v[230:233], v[8:11]
	v_mfma_f32_16x16x32_bf16 v[88:91], v[138:141], v[154:157], v[88:91]
	v_mfma_f32_16x16x32_bf16 v[24:27], v[146:149], v[154:157], v[24:27]
	v_mfma_f32_16x16x32_bf16 v[80:83], v[138:141], v[170:173], v[80:83]
	v_mfma_f32_16x16x32_bf16 v[16:19], v[146:149], v[170:173], v[16:19]
	v_mfma_f32_16x16x32_bf16 v[68:71], v[138:141], v[204:207], v[68:71]
	v_mfma_f32_16x16x32_bf16 v[4:7], v[146:149], v[204:207], v[4:7]
	v_mfma_f32_16x16x32_bf16 v[64:67], v[138:141], v[226:229], v[64:67]
	v_mfma_f32_16x16x32_bf16 v[0:3], v[146:149], v[226:229], v[0:3]
	v_mfma_f32_16x16x32_bf16 v[88:91], v[142:145], v[166:169], v[88:91]
	v_mfma_f32_16x16x32_bf16 v[24:27], v[150:153], v[166:169], v[24:27]
	v_mfma_f32_16x16x32_bf16 v[80:83], v[142:145], v[174:177], v[80:83]
	v_mfma_f32_16x16x32_bf16 v[16:19], v[150:153], v[174:177], v[16:19]
	v_mfma_f32_16x16x32_bf16 v[68:71], v[142:145], v[208:211], v[68:71]
	v_mfma_f32_16x16x32_bf16 v[4:7], v[150:153], v[208:211], v[4:7]
	v_mfma_f32_16x16x32_bf16 v[64:67], v[142:145], v[230:233], v[64:67]
	v_mfma_f32_16x16x32_bf16 v[0:3], v[150:153], v[230:233], v[0:3]
	s_barrier
; #define PG8_STAGE(bufoff, gbase, voff) do { _Pragma("unroll") for (int _i = 0; _i < 2; ++_i) \
;         __builtin_amdgcn_global_load_lds((const unsigned*)((const char*)(gbase) + (voff)[_i]), (PG8_LAS unsigned*)(lds + (bufoff) + ldsw + _i * 8192), 16, 0, 0); } while (0)
; #define PG8_LDA(dst, b, h) do { _Pragma("unroll") for (int m = 0; m < 4; ++m) _Pragma("unroll") for (int k = 0; k < 2; ++k) dst[m][k] = *(const PG8_LAS bf16x8*)(lds + PG8_SA(b, h) + aoff + m * 2048 + k * 1024); } while (0)
; #define PG8_LDB(dst, b, h) do { _Pragma("unroll") for (int n = 0; n < 2; ++n) _Pragma("unroll") for (int k = 0; k < 2; ++k) dst[n][k] = *(const PG8_LAS bf16x8*)(lds + PG8_SB(b, h) + boff + n * 2048 + k * 1024); } while (0)
; template <class Epi, class Sched, bool ALIGN_EPI = false, bool SP2 = false>
; __device__ __forceinline__ void gemm_phase(PG8_LAS unsigned char* lds, const Gemm g, const Sched& S, const Epi& E) {
;     ...
;         for (int t = 0; t < nt; t += 2) {
;             const bool last = (t == nt - 2);
;             const char* a1 = cA + (size_t)(t + 1) * kstep;
;             const char* a2 = last ? nA : cA + (size_t)(t + 2) * kstep; const char* b2 = last ? nB : cB + (size_t)(t + 2) * kstep;
;             const char* a3 = a2 + kstep; const char* b3 = b2 + kstep;
;             if (last && has_next) S.a_ready(nxt);
;             if constexpr (SP2) {
;             PG8_LDB(B0, 0, 0); PG8_LDB(B1, 0, 1); PG8_SCHED; PG8_LDA(At, 0, 0); PG8_STAGE(PG8_SA(1, 1), a1 + hstep, voffA);
;             PG8_WAIT_V(8); PG8_WAIT_L(0); PG8_BAR; PG8_MMA(0, 0, At, B0); PG8_MMA(0, 1, At, B1); PG8_BAR; PG8_SCHED;
;             PG8_LDA(At, 0, 1); PG8_STAGE(PG8_SB(0, 0), b2, voffB); PG8_STAGE(PG8_SB(0, 1), b2 + hstep, voffB); PG8_STAGE(PG8_SA(0, 0), a2, voffA);
;             PG8_WAIT_V(8); PG8_WAIT_L(0); PG8_BAR; PG8_MMA(1, 0, At, B0); PG8_MMA(1, 1, At, B1); PG8_BAR; PG8_SCHED;
;             PG8_LDB(B0, 1, 0); PG8_LDB(B1, 1, 1); PG8_SCHED; PG8_LDA(At, 1, 0); PG8_STAGE(PG8_SA(0, 1), a2 + hstep, voffA);
;             PG8_WAIT_V(8); PG8_WAIT_L(0); PG8_BAR; PG8_MMA(0, 0, At, B0); PG8_MMA(0, 1, At, B1); PG8_BAR; PG8_SCHED;
;             PG8_LDA(At, 1, 1); PG8_STAGE(PG8_SB(1, 0), b3, voffB); PG8_STAGE(PG8_SB(1, 1), b3 + hstep, voffB); PG8_STAGE(PG8_SA(1, 0), a3, voffA);
;             PG8_WAIT_V(8); PG8_WAIT_L(0); PG8_BAR; PG8_MMA(1, 0, At, B0); PG8_MMA(1, 1, At, B1); PG8_BAR; PG8_SCHED;
	s_add_i32 s71, 0, 0x18000
	v_add_u32_e32 v116, s71, v213
	s_add_i32 s88, 0, 0x1c000
	ds_read_b128 v[118:121], v116
	ds_read_b128 v[126:129], v116 offset:1024
	ds_read_b128 v[130:133], v116 offset:2048
	ds_read_b128 v[134:137], v116 offset:3072
	v_add_u32_e32 v116, s88, v213
	ds_read_b128 v[138:141], v116
	ds_read_b128 v[142:145], v116 offset:1024
	ds_read_b128 v[146:149], v116 offset:2048
	ds_read_b128 v[150:153], v116 offset:3072
	s_add_u32 s30, s74, 0x80000
	s_addc_u32 s31, s75, 0
	s_mov_b32 m0, s79
	ds_read_b128 v[154:157], v219 offset:32768
	ds_read_b128 v[166:169], v219 offset:33792
	ds_read_b128 v[170:173], v219 offset:34816
	ds_read_b128 v[174:177], v219 offset:35840
	ds_read_b128 v[204:207], v219 offset:36864
	ds_read_b128 v[208:211], v219 offset:37888
	ds_read_b128 v[226:229], v219 offset:38912
	ds_read_b128 v[230:233], v219 offset:39936
	global_load_lds_dwordx4 v186, s[30:31]
	s_mov_b32 m0, s80
	s_nop 0
	global_load_lds_dwordx4 v182, s[30:31]
	s_waitcnt vmcnt(8)
	s_waitcnt lgkmcnt(0)
	s_barrier
	s_waitcnt lgkmcnt(0)
	v_mfma_f32_16x16x32_bf16 v[162:165], v[118:121], v[154:157], v[162:165]
	v_mfma_f32_16x16x32_bf16 v[60:63], v[130:133], v[154:157], v[60:63]
	v_mfma_f32_16x16x32_bf16 v[122:125], v[118:121], v[170:173], v[122:125]
	v_mfma_f32_16x16x32_bf16 v[52:55], v[130:133], v[170:173], v[52:55]
	v_mfma_f32_16x16x32_bf16 v[108:111], v[118:121], v[204:207], v[108:111]
	v_mfma_f32_16x16x32_bf16 v[44:47], v[130:133], v[204:207], v[44:47]
	v_mfma_f32_16x16x32_bf16 v[104:107], v[118:121], v[226:229], v[104:107]
	v_mfma_f32_16x16x32_bf16 v[40:43], v[130:133], v[226:229], v[40:43]
	v_mfma_f32_16x16x32_bf16 v[162:165], v[126:129], v[166:169], v[162:165]
	v_mfma_f32_16x16x32_bf16 v[60:63], v[134:137], v[166:169], v[60:63]
	v_mfma_f32_16x16x32_bf16 v[122:125], v[126:129], v[174:177], v[122:125]
	v_mfma_f32_16x16x32_bf16 v[52:55], v[134:137], v[174:177], v[52:55]
	v_mfma_f32_16x16x32_bf16 v[108:111], v[126:129], v[208:211], v[108:111]
	v_mfma_f32_16x16x32_bf16 v[44:47], v[134:137], v[208:211], v[44:47]
	v_mfma_f32_16x16x32_bf16 v[104:107], v[126:129], v[230:233], v[104:107]
	v_mfma_f32_16x16x32_bf16 v[40:43], v[134:137], v[230:233], v[40:43]
	v_mfma_f32_16x16x32_bf16 v[158:161], v[138:141], v[154:157], v[158:161]
	v_mfma_f32_16x16x32_bf16 v[56:59], v[146:149], v[154:157], v[56:59]
	v_mfma_f32_16x16x32_bf16 v[112:115], v[138:141], v[170:173], v[112:115]
	v_mfma_f32_16x16x32_bf16 v[48:51], v[146:149], v[170:173], v[48:51]
	v_mfma_f32_16x16x32_bf16 v[100:103], v[138:141], v[204:207], v[100:103]
	v_mfma_f32_16x16x32_bf16 v[36:39], v[146:149], v[204:207], v[36:39]
	v_mfma_f32_16x16x32_bf16 v[96:99], v[138:141], v[226:229], v[96:99]
	v_mfma_f32_16x16x32_bf16 v[32:35], v[146:149], v[226:229], v[32:35]
	v_mfma_f32_16x16x32_bf16 v[158:161], v[142:145], v[166:169], v[158:161]
	v_mfma_f32_16x16x32_bf16 v[56:59], v[150:153], v[166:169], v[56:59]
	v_mfma_f32_16x16x32_bf16 v[114:117], v[142:145], v[174:177], v[112:115]
	v_mfma_f32_16x16x32_bf16 v[48:51], v[150:153], v[174:177], v[48:51]
	v_mfma_f32_16x16x32_bf16 v[100:103], v[142:145], v[208:211], v[100:103]
	v_mfma_f32_16x16x32_bf16 v[36:39], v[150:153], v[208:211], v[36:39]
	v_mfma_f32_16x16x32_bf16 v[96:99], v[142:145], v[230:233], v[96:99]
	v_mfma_f32_16x16x32_bf16 v[32:35], v[150:153], v[230:233], v[32:35]
	s_barrier
	s_add_i32 s30, s71, s29
	s_mov_b32 m0, s30
	ds_read_b128 v[154:157], v219 offset:49152
	ds_read_b128 v[166:169], v219 offset:50176
	ds_read_b128 v[170:173], v219 offset:51200
	ds_read_b128 v[174:177], v219 offset:52224
	ds_read_b128 v[204:207], v219 offset:53248
	ds_read_b128 v[208:211], v219 offset:54272
	ds_read_b128 v[226:229], v219 offset:55296
	ds_read_b128 v[230:233], v219 offset:56320
	s_add_u32 s52, s72, 0x80
	s_addc_u32 s53, s73, 0
	global_load_lds_dwordx4 v184, s[52:53]
	s_add_i32 m0, s30, 0x2000
	s_add_u32 s30, s72, 0x80080
	s_addc_u32 s31, s73, 0
	s_add_i32 s71, s88, s29
	global_load_lds_dwordx4 v180, s[52:53]
	s_mov_b32 m0, s71
	s_nop 0
	global_load_lds_dwordx4 v184, s[30:31]
	s_add_i32 m0, s71, 0x2000
	s_nop 0
	global_load_lds_dwordx4 v180, s[30:31]
	s_mov_b32 m0, s83
	s_nop 0
	s_add_u32 s52, s74, 0x80
	s_addc_u32 s53, s75, 0
	global_load_lds_dwordx4 v186, s[52:53]
	s_mov_b32 m0, s84
	s_nop 0
	global_load_lds_dwordx4 v182, s[52:53]
	s_waitcnt vmcnt(8)
	s_waitcnt lgkmcnt(0)
	s_barrier
	s_waitcnt lgkmcnt(0)
	v_mfma_f32_16x16x32_bf16 v[92:95], v[118:121], v[154:157], v[92:95]
	v_mfma_f32_16x16x32_bf16 v[28:31], v[130:133], v[154:157], v[28:31]
	v_mfma_f32_16x16x32_bf16 v[84:87], v[118:121], v[170:173], v[84:87]
	v_mfma_f32_16x16x32_bf16 v[20:23], v[130:133], v[170:173], v[20:23]
	v_mfma_f32_16x16x32_bf16 v[76:79], v[118:121], v[204:207], v[76:79]
	v_mfma_f32_16x16x32_bf16 v[12:15], v[130:133], v[204:207], v[12:15]
	v_mfma_f32_16x16x32_bf16 v[72:75], v[118:121], v[226:229], v[72:75]
	v_mfma_f32_16x16x32_bf16 v[8:11], v[130:133], v[226:229], v[8:11]
	v_mfma_f32_16x16x32_bf16 v[92:95], v[126:129], v[166:169], v[92:95]
	v_mfma_f32_16x16x32_bf16 v[28:31], v[134:137], v[166:169], v[28:31]
	v_mfma_f32_16x16x32_bf16 v[84:87], v[126:129], v[174:177], v[84:87]
	v_mfma_f32_16x16x32_bf16 v[20:23], v[134:137], v[174:177], v[20:23]
	v_mfma_f32_16x16x32_bf16 v[76:79], v[126:129], v[208:211], v[76:79]
	v_mfma_f32_16x16x32_bf16 v[12:15], v[134:137], v[208:211], v[12:15]
	v_mfma_f32_16x16x32_bf16 v[72:75], v[126:129], v[230:233], v[72:75]
	v_mfma_f32_16x16x32_bf16 v[8:11], v[134:137], v[230:233], v[8:11]
	v_mfma_f32_16x16x32_bf16 v[88:91], v[138:141], v[154:157], v[88:91]
	v_mfma_f32_16x16x32_bf16 v[24:27], v[146:149], v[154:157], v[24:27]
	v_mfma_f32_16x16x32_bf16 v[80:83], v[138:141], v[170:173], v[80:83]
	v_mfma_f32_16x16x32_bf16 v[16:19], v[146:149], v[170:173], v[16:19]
	v_mfma_f32_16x16x32_bf16 v[68:71], v[138:141], v[204:207], v[68:71]
	v_mfma_f32_16x16x32_bf16 v[4:7], v[146:149], v[204:207], v[4:7]
	v_mfma_f32_16x16x32_bf16 v[64:67], v[138:141], v[226:229], v[64:67]
	v_mfma_f32_16x16x32_bf16 v[0:3], v[146:149], v[226:229], v[0:3]
	v_mfma_f32_16x16x32_bf16 v[88:91], v[142:145], v[166:169], v[88:91]
	v_mfma_f32_16x16x32_bf16 v[24:27], v[150:153], v[166:169], v[24:27]
	v_mfma_f32_16x16x32_bf16 v[80:83], v[142:145], v[174:177], v[80:83]
	v_mfma_f32_16x16x32_bf16 v[16:19], v[150:153], v[174:177], v[16:19]
	v_mfma_f32_16x16x32_bf16 v[68:71], v[142:145], v[208:211], v[68:71]
	v_mfma_f32_16x16x32_bf16 v[4:7], v[150:153], v[208:211], v[4:7]
	v_mfma_f32_16x16x32_bf16 v[64:67], v[142:145], v[230:233], v[64:67]
	v_mfma_f32_16x16x32_bf16 v[0:3], v[150:153], v[230:233], v[0:3]
	s_barrier
	s_add_i32 s65, s65, 2
	s_add_u32 s10, s10, 0x100
	s_addc_u32 s11, s11, 0
	s_add_u32 s47, s47, 0x100
	s_addc_u32 s63, s63, 0
	s_cmp_gt_u32 s65, 29
	s_cbranch_scc0 .LBB0_404
	s_and_b64 vcc, exec, s[54:55]
	s_cbranch_vccz .LBB0_407
	s_barrier

; #define PG8_STAGE(bufoff, gbase, voff) do { _Pragma("unroll") for (int _i = 0; _i < 2; ++_i) \
;         __builtin_amdgcn_global_load_lds((const unsigned*)((const char*)(gbase) + (voff)[_i]), (PG8_LAS unsigned*)(lds + (bufoff) + ldsw + _i * 8192), 16, 0, 0); } while (0)
; #define PG8_LDA(dst, b, h) do { _Pragma("unroll") for (int m = 0; m < 4; ++m) _Pragma("unroll") for (int k = 0; k < 2; ++k) dst[m][k] = *(const PG8_LAS bf16x8*)(lds + PG8_SA(b, h) + aoff + m * 2048 + k * 1024); } while (0)
; #define PG8_LDB(dst, b, h) do { _Pragma("unroll") for (int n = 0; n < 2; ++n) _Pragma("unroll") for (int k = 0; k < 2; ++k) dst[n][k] = *(const PG8_LAS bf16x8*)(lds + PG8_SB(b, h) + boff + n * 2048 + k * 1024); } while (0)
; template <class Epi, class Sched, bool ALIGN_EPI = false, bool SP2 = false>
; __device__ __forceinline__ void gemm_phase(PG8_LAS unsigned char* lds, const Gemm g, const Sched& S, const Epi& E) {
;     ...
;         for (int t = 0; t < nt; t += 2) {
;             const bool last = (t == nt - 2);
;             const char* a1 = cA + (size_t)(t + 1) * kstep;
;             const char* a2 = last ? nA : cA + (size_t)(t + 2) * kstep; const char* b2 = last ? nB : cB + (size_t)(t + 2) * kstep;
;             const char* a3 = a2 + kstep; const char* b3 = b2 + kstep;
;             if (last && has_next) S.a_ready(nxt);
;             if constexpr (SP2) {
;             PG8_LDB(B0, 0, 0); PG8_LDB(B1, 0, 1); PG8_SCHED; PG8_LDA(At, 0, 0); PG8_STAGE(PG8_SA(1, 1), a1 + hstep, voffA);
;             PG8_WAIT_V(8); PG8_WAIT_L(0); PG8_BAR; PG8_MMA(0, 0, At, B0); PG8_MMA(0, 1, At, B1); PG8_BAR; PG8_SCHED;
;             PG8_LDA(At, 0, 1); PG8_STAGE(PG8_SB(0, 0), b2, voffB); PG8_STAGE(PG8_SB(0, 1), b2 + hstep, voffB); PG8_STAGE(PG8_SA(0, 0), a2, voffA);
;             PG8_WAIT_V(8); PG8_WAIT_L(0); PG8_BAR; PG8_MMA(1, 0, At, B0); PG8_MMA(1, 1, At, B1); PG8_BAR; PG8_SCHED;
;             PG8_LDB(B0, 1, 0); PG8_LDB(B1, 1, 1); PG8_SCHED; PG8_LDA(At, 1, 0); PG8_STAGE(PG8_SA(0, 1), a2 + hstep, voffA);
;             PG8_WAIT_V(8); PG8_WAIT_L(0); PG8_BAR; PG8_MMA(0, 0, At, B0); PG8_MMA(0, 1, At, B1); PG8_BAR; PG8_SCHED;
;             PG8_LDA(At, 1, 1); PG8_STAGE(PG8_SB(1, 0), b3, voffB); PG8_STAGE(PG8_SB(1, 1), b3 + hstep, voffB); PG8_STAGE(PG8_SA(1, 0), a3, voffA);
;             PG8_WAIT_V(8); PG8_WAIT_L(0); PG8_BAR; PG8_MMA(1, 0, At, B0); PG8_MMA(1, 1, At, B1); PG8_BAR; PG8_SCHED;
.LBB0_552:
	ds_read_b128 v[152:155], v149
	ds_read_b128 v[156:159], v149 offset:1024
	ds_read_b128 v[160:163], v149 offset:2048
	ds_read_b128 v[164:167], v149 offset:3072
	ds_read_b128 v[168:171], v150
	ds_read_b128 v[172:175], v150 offset:1024
	ds_read_b128 v[180:183], v150 offset:2048
	ds_read_b128 v[184:187], v150 offset:3072
	s_add_u32 s34, s26, 0x100
	s_addc_u32 s35, s27, 0
	s_cmpk_eq_i32 s67, 0x54
	s_cselect_b32 s45, s7, s35
	s_cselect_b32 s44, s6, s34
	s_cselect_b32 s37, s9, s66
	s_cselect_b32 s36, s8, s65
	s_add_i32 m0, s29, 0xc000
	ds_read_b128 v[188:191], v151
	ds_read_b128 v[192:195], v151 offset:1024
	ds_read_b128 v[196:199], v151 offset:2048
	ds_read_b128 v[200:203], v151 offset:3072
	ds_read_b128 v[204:207], v151 offset:4096
	ds_read_b128 v[208:211], v151 offset:5120
	ds_read_b128 v[212:215], v151 offset:6144
	ds_read_b128 v[216:219], v151 offset:7168
	global_load_lds_dwordx4 v136, s[26:27]
	s_add_i32 m0, s29, 0xe000
	s_nop 0
	global_load_lds_dwordx4 v138, s[26:27]
	s_waitcnt vmcnt(8)
	s_waitcnt lgkmcnt(0)
	s_barrier
	s_waitcnt lgkmcnt(0)
	v_mfma_f32_16x16x32_bf16 v[124:127], v[152:155], v[188:191], v[124:127]
	v_mfma_f32_16x16x32_bf16 v[120:123], v[160:163], v[188:191], v[120:123]
	v_mfma_f32_16x16x32_bf16 v[116:119], v[152:155], v[196:199], v[116:119]
	v_mfma_f32_16x16x32_bf16 v[108:111], v[160:163], v[196:199], v[108:111]
	v_mfma_f32_16x16x32_bf16 v[100:103], v[152:155], v[204:207], v[100:103]
	v_mfma_f32_16x16x32_bf16 v[92:95], v[160:163], v[204:207], v[92:95]
	v_mfma_f32_16x16x32_bf16 v[84:87], v[152:155], v[212:215], v[84:87]
	v_mfma_f32_16x16x32_bf16 v[76:79], v[160:163], v[212:215], v[76:79]
	v_mfma_f32_16x16x32_bf16 v[124:127], v[156:159], v[192:195], v[124:127]
	v_mfma_f32_16x16x32_bf16 v[120:123], v[164:167], v[192:195], v[120:123]
	v_mfma_f32_16x16x32_bf16 v[116:119], v[156:159], v[200:203], v[116:119]
	v_mfma_f32_16x16x32_bf16 v[108:111], v[164:167], v[200:203], v[108:111]
	v_mfma_f32_16x16x32_bf16 v[100:103], v[156:159], v[208:211], v[100:103]
	v_mfma_f32_16x16x32_bf16 v[92:95], v[164:167], v[208:211], v[92:95]
	v_mfma_f32_16x16x32_bf16 v[84:87], v[156:159], v[216:219], v[84:87]
	v_mfma_f32_16x16x32_bf16 v[76:79], v[164:167], v[216:219], v[76:79]
	v_mfma_f32_16x16x32_bf16 v[112:115], v[168:171], v[188:191], v[112:115]
	v_mfma_f32_16x16x32_bf16 v[104:107], v[180:183], v[188:191], v[104:107]
	v_mfma_f32_16x16x32_bf16 v[96:99], v[168:171], v[196:199], v[96:99]
	v_mfma_f32_16x16x32_bf16 v[88:91], v[180:183], v[196:199], v[88:91]
	v_mfma_f32_16x16x32_bf16 v[80:83], v[168:171], v[204:207], v[80:83]
	v_mfma_f32_16x16x32_bf16 v[72:75], v[180:183], v[204:207], v[72:75]
	v_mfma_f32_16x16x32_bf16 v[68:71], v[168:171], v[212:215], v[68:71]
	v_mfma_f32_16x16x32_bf16 v[64:67], v[180:183], v[212:215], v[64:67]
	v_mfma_f32_16x16x32_bf16 v[112:115], v[172:175], v[192:195], v[112:115]
	v_mfma_f32_16x16x32_bf16 v[104:107], v[184:187], v[192:195], v[104:107]
	v_mfma_f32_16x16x32_bf16 v[96:99], v[172:175], v[200:203], v[96:99]
	v_mfma_f32_16x16x32_bf16 v[88:91], v[184:187], v[200:203], v[88:91]
	v_mfma_f32_16x16x32_bf16 v[80:83], v[172:175], v[208:211], v[80:83]
	v_mfma_f32_16x16x32_bf16 v[72:75], v[184:187], v[208:211], v[72:75]
	v_mfma_f32_16x16x32_bf16 v[68:71], v[172:175], v[216:219], v[68:71]
	v_mfma_f32_16x16x32_bf16 v[64:67], v[184:187], v[216:219], v[64:67]
	s_barrier
	s_add_i32 s26, s55, s1
	s_mov_b32 m0, s26
	ds_read_b128 v[188:191], v151 offset:16384
	ds_read_b128 v[192:195], v151 offset:17408
	ds_read_b128 v[196:199], v151 offset:18432
	ds_read_b128 v[200:203], v151 offset:19456
	ds_read_b128 v[204:207], v151 offset:20480
	ds_read_b128 v[208:211], v151 offset:21504
	ds_read_b128 v[212:215], v151 offset:22528
	ds_read_b128 v[216:219], v151 offset:23552
	global_load_lds_dwordx4 v130, s[36:37]
	s_add_i32 m0, s26, 0x2000
	s_add_u32 s26, s36, 0x160000
	s_addc_u32 s27, s37, 0
	s_add_i32 s30, s56, s1
	global_load_lds_dwordx4 v134, s[36:37]
	s_mov_b32 m0, s30
	s_nop 0
	global_load_lds_dwordx4 v130, s[26:27]
	s_add_i32 m0, s30, 0x2000
	s_nop 0
	global_load_lds_dwordx4 v134, s[26:27]
	s_mov_b32 m0, s29
	s_nop 0
	global_load_lds_dwordx4 v128, s[44:45]
	s_mov_b32 m0, s33
	s_nop 0
	global_load_lds_dwordx4 v132, s[44:45]
	s_waitcnt vmcnt(8)
	s_waitcnt lgkmcnt(0)
	s_barrier
	s_waitcnt lgkmcnt(0)
	v_mfma_f32_16x16x32_bf16 v[60:63], v[152:155], v[188:191], v[60:63]
	v_mfma_f32_16x16x32_bf16 v[56:59], v[160:163], v[188:191], v[56:59]
	v_mfma_f32_16x16x32_bf16 v[52:55], v[152:155], v[196:199], v[52:55]
	v_mfma_f32_16x16x32_bf16 v[44:47], v[160:163], v[196:199], v[44:47]
	v_mfma_f32_16x16x32_bf16 v[36:39], v[152:155], v[204:207], v[36:39]
	v_mfma_f32_16x16x32_bf16 v[28:31], v[160:163], v[204:207], v[28:31]
	v_mfma_f32_16x16x32_bf16 v[20:23], v[152:155], v[212:215], v[20:23]
	v_mfma_f32_16x16x32_bf16 v[12:15], v[160:163], v[212:215], v[12:15]
	v_mfma_f32_16x16x32_bf16 v[60:63], v[156:159], v[192:195], v[60:63]
	v_mfma_f32_16x16x32_bf16 v[56:59], v[164:167], v[192:195], v[56:59]
	v_mfma_f32_16x16x32_bf16 v[52:55], v[156:159], v[200:203], v[52:55]
	v_mfma_f32_16x16x32_bf16 v[44:47], v[164:167], v[200:203], v[44:47]
	v_mfma_f32_16x16x32_bf16 v[36:39], v[156:159], v[208:211], v[36:39]
	v_mfma_f32_16x16x32_bf16 v[28:31], v[164:167], v[208:211], v[28:31]
	v_mfma_f32_16x16x32_bf16 v[20:23], v[156:159], v[216:219], v[20:23]
	v_mfma_f32_16x16x32_bf16 v[12:15], v[164:167], v[216:219], v[12:15]
	v_mfma_f32_16x16x32_bf16 v[48:51], v[168:171], v[188:191], v[48:51]
	v_mfma_f32_16x16x32_bf16 v[40:43], v[180:183], v[188:191], v[40:43]
	v_mfma_f32_16x16x32_bf16 v[32:35], v[168:171], v[196:199], v[32:35]
	v_mfma_f32_16x16x32_bf16 v[24:27], v[180:183], v[196:199], v[24:27]
	v_mfma_f32_16x16x32_bf16 v[16:19], v[168:171], v[204:207], v[16:19]
	v_mfma_f32_16x16x32_bf16 v[8:11], v[180:183], v[204:207], v[8:11]
	v_mfma_f32_16x16x32_bf16 v[4:7], v[168:171], v[212:215], v[4:7]
	v_mfma_f32_16x16x32_bf16 v[0:3], v[180:183], v[212:215], v[0:3]
	v_mfma_f32_16x16x32_bf16 v[48:51], v[172:175], v[192:195], v[48:51]
	v_mfma_f32_16x16x32_bf16 v[40:43], v[184:187], v[192:195], v[40:43]
	v_mfma_f32_16x16x32_bf16 v[32:35], v[172:175], v[200:203], v[32:35]
	v_mfma_f32_16x16x32_bf16 v[24:27], v[184:187], v[200:203], v[24:27]
	v_mfma_f32_16x16x32_bf16 v[16:19], v[172:175], v[208:211], v[16:19]
	v_mfma_f32_16x16x32_bf16 v[8:11], v[184:187], v[208:211], v[8:11]
	v_mfma_f32_16x16x32_bf16 v[4:7], v[172:175], v[216:219], v[4:7]
	v_mfma_f32_16x16x32_bf16 v[0:3], v[184:187], v[216:219], v[0:3]
	s_barrier
; #define PG8_STAGE(bufoff, gbase, voff) do { _Pragma("unroll") for (int _i = 0; _i < 2; ++_i) \
;         __builtin_amdgcn_global_load_lds((const unsigned*)((const char*)(gbase) + (voff)[_i]), (PG8_LAS unsigned*)(lds + (bufoff) + ldsw + _i * 8192), 16, 0, 0); } while (0)
; #define PG8_LDA(dst, b, h) do { _Pragma("unroll") for (int m = 0; m < 4; ++m) _Pragma("unroll") for (int k = 0; k < 2; ++k) dst[m][k] = *(const PG8_LAS bf16x8*)(lds + PG8_SA(b, h) + aoff + m * 2048 + k * 1024); } while (0)
; #define PG8_LDB(dst, b, h) do { _Pragma("unroll") for (int n = 0; n < 2; ++n) _Pragma("unroll") for (int k = 0; k < 2; ++k) dst[n][k] = *(const PG8_LAS bf16x8*)(lds + PG8_SB(b, h) + boff + n * 2048 + k * 1024); } while (0)
; template <class Epi, class Sched, bool ALIGN_EPI = false, bool SP2 = false>
; __device__ __forceinline__ void gemm_phase(PG8_LAS unsigned char* lds, const Gemm g, const Sched& S, const Epi& E) {
;     ...
;         for (int t = 0; t < nt; t += 2) {
;             const bool last = (t == nt - 2);
;             const char* a1 = cA + (size_t)(t + 1) * kstep;
;             const char* a2 = last ? nA : cA + (size_t)(t + 2) * kstep; const char* b2 = last ? nB : cB + (size_t)(t + 2) * kstep;
;             const char* a3 = a2 + kstep; const char* b3 = b2 + kstep;
;             if (last && has_next) S.a_ready(nxt);
;             if constexpr (SP2) {
;             PG8_LDB(B0, 0, 0); PG8_LDB(B1, 0, 1); PG8_SCHED; PG8_LDA(At, 0, 0); PG8_STAGE(PG8_SA(1, 1), a1 + hstep, voffA);
;             PG8_WAIT_V(8); PG8_WAIT_L(0); PG8_BAR; PG8_MMA(0, 0, At, B0); PG8_MMA(0, 1, At, B1); PG8_BAR; PG8_SCHED;
;             PG8_LDA(At, 0, 1); PG8_STAGE(PG8_SB(0, 0), b2, voffB); PG8_STAGE(PG8_SB(0, 1), b2 + hstep, voffB); PG8_STAGE(PG8_SA(0, 0), a2, voffA);
;             PG8_WAIT_V(8); PG8_WAIT_L(0); PG8_BAR; PG8_MMA(1, 0, At, B0); PG8_MMA(1, 1, At, B1); PG8_BAR; PG8_SCHED;
;             PG8_LDB(B0, 1, 0); PG8_LDB(B1, 1, 1); PG8_SCHED; PG8_LDA(At, 1, 0); PG8_STAGE(PG8_SA(0, 1), a2 + hstep, voffA);
;             PG8_WAIT_V(8); PG8_WAIT_L(0); PG8_BAR; PG8_MMA(0, 0, At, B0); PG8_MMA(0, 1, At, B1); PG8_BAR; PG8_SCHED;
;             PG8_LDA(At, 1, 1); PG8_STAGE(PG8_SB(1, 0), b3, voffB); PG8_STAGE(PG8_SB(1, 1), b3 + hstep, voffB); PG8_STAGE(PG8_SA(1, 0), a3, voffA);
;             PG8_WAIT_V(8); PG8_WAIT_L(0); PG8_BAR; PG8_MMA(1, 0, At, B0); PG8_MMA(1, 1, At, B1); PG8_BAR; PG8_SCHED;
	s_add_i32 s30, 0, 0x18000
	s_add_i32 s31, 0, 0x1c000
	v_add_u32_e32 v164, s30, v147
	v_add_u32_e32 v184, s31, v147
	ds_read_b128 v[152:155], v164
	ds_read_b128 v[156:159], v164 offset:1024
	ds_read_b128 v[160:163], v164 offset:2048
	ds_read_b128 v[164:167], v164 offset:3072
	ds_read_b128 v[168:171], v184
	ds_read_b128 v[172:175], v184 offset:1024
	ds_read_b128 v[180:183], v184 offset:2048
	ds_read_b128 v[184:187], v184 offset:3072
	s_add_u32 s26, s44, 0x160000
	s_addc_u32 s27, s45, 0
	s_mov_b32 m0, s46
	ds_read_b128 v[188:191], v151 offset:32768
	ds_read_b128 v[192:195], v151 offset:33792
	ds_read_b128 v[196:199], v151 offset:34816
	ds_read_b128 v[200:203], v151 offset:35840
	ds_read_b128 v[204:207], v151 offset:36864
	ds_read_b128 v[208:211], v151 offset:37888
	ds_read_b128 v[212:215], v151 offset:38912
	ds_read_b128 v[216:219], v151 offset:39936
	global_load_lds_dwordx4 v128, s[26:27]
	s_mov_b32 m0, s47
	s_nop 0
	global_load_lds_dwordx4 v132, s[26:27]
	s_waitcnt vmcnt(8)
	s_waitcnt lgkmcnt(0)
	s_barrier
	s_waitcnt lgkmcnt(0)
	v_mfma_f32_16x16x32_bf16 v[124:127], v[152:155], v[188:191], v[124:127]
	v_mfma_f32_16x16x32_bf16 v[120:123], v[160:163], v[188:191], v[120:123]
	v_mfma_f32_16x16x32_bf16 v[116:119], v[152:155], v[196:199], v[116:119]
	v_mfma_f32_16x16x32_bf16 v[108:111], v[160:163], v[196:199], v[108:111]
	v_mfma_f32_16x16x32_bf16 v[100:103], v[152:155], v[204:207], v[100:103]
	v_mfma_f32_16x16x32_bf16 v[92:95], v[160:163], v[204:207], v[92:95]
	v_mfma_f32_16x16x32_bf16 v[84:87], v[152:155], v[212:215], v[84:87]
	v_mfma_f32_16x16x32_bf16 v[76:79], v[160:163], v[212:215], v[76:79]
	v_mfma_f32_16x16x32_bf16 v[124:127], v[156:159], v[192:195], v[124:127]
	v_mfma_f32_16x16x32_bf16 v[120:123], v[164:167], v[192:195], v[120:123]
	v_mfma_f32_16x16x32_bf16 v[116:119], v[156:159], v[200:203], v[116:119]
	v_mfma_f32_16x16x32_bf16 v[108:111], v[164:167], v[200:203], v[108:111]
	v_mfma_f32_16x16x32_bf16 v[100:103], v[156:159], v[208:211], v[100:103]
	v_mfma_f32_16x16x32_bf16 v[92:95], v[164:167], v[208:211], v[92:95]
	v_mfma_f32_16x16x32_bf16 v[84:87], v[156:159], v[216:219], v[84:87]
	v_mfma_f32_16x16x32_bf16 v[76:79], v[164:167], v[216:219], v[76:79]
	v_mfma_f32_16x16x32_bf16 v[112:115], v[168:171], v[188:191], v[112:115]
	v_mfma_f32_16x16x32_bf16 v[104:107], v[180:183], v[188:191], v[104:107]
	v_mfma_f32_16x16x32_bf16 v[96:99], v[168:171], v[196:199], v[96:99]
	v_mfma_f32_16x16x32_bf16 v[88:91], v[180:183], v[196:199], v[88:91]
	v_mfma_f32_16x16x32_bf16 v[80:83], v[168:171], v[204:207], v[80:83]
	v_mfma_f32_16x16x32_bf16 v[72:75], v[180:183], v[204:207], v[72:75]
	v_mfma_f32_16x16x32_bf16 v[68:71], v[168:171], v[212:215], v[68:71]
	v_mfma_f32_16x16x32_bf16 v[64:67], v[180:183], v[212:215], v[64:67]
	v_mfma_f32_16x16x32_bf16 v[112:115], v[172:175], v[192:195], v[112:115]
	v_mfma_f32_16x16x32_bf16 v[104:107], v[184:187], v[192:195], v[104:107]
	v_mfma_f32_16x16x32_bf16 v[96:99], v[172:175], v[200:203], v[96:99]
	v_mfma_f32_16x16x32_bf16 v[88:91], v[184:187], v[200:203], v[88:91]
	v_mfma_f32_16x16x32_bf16 v[80:83], v[172:175], v[208:211], v[80:83]
	v_mfma_f32_16x16x32_bf16 v[72:75], v[184:187], v[208:211], v[72:75]
	v_mfma_f32_16x16x32_bf16 v[68:71], v[172:175], v[216:219], v[68:71]
	v_mfma_f32_16x16x32_bf16 v[64:67], v[184:187], v[216:219], v[64:67]
	s_barrier
	s_add_i32 s26, s30, s1
	s_mov_b32 m0, s26
	ds_read_b128 v[188:191], v151 offset:49152
	ds_read_b128 v[192:195], v151 offset:50176
	ds_read_b128 v[196:199], v151 offset:51200
	ds_read_b128 v[200:203], v151 offset:52224
	ds_read_b128 v[204:207], v151 offset:53248
	ds_read_b128 v[208:211], v151 offset:54272
	ds_read_b128 v[212:215], v151 offset:55296
	ds_read_b128 v[216:219], v151 offset:56320
	s_add_u32 s10, s36, 0x80
	s_addc_u32 s11, s37, 0
	global_load_lds_dwordx4 v130, s[10:11]
	s_add_i32 m0, s26, 0x2000
	s_add_u32 s26, s36, 0x160080
	s_addc_u32 s27, s37, 0
	s_add_i32 s30, s31, s1
	global_load_lds_dwordx4 v134, s[10:11]
	s_mov_b32 m0, s30
	s_nop 0
	global_load_lds_dwordx4 v130, s[26:27]
	s_add_i32 m0, s30, 0x2000
	s_nop 0
	global_load_lds_dwordx4 v134, s[26:27]
	s_mov_b32 m0, s53
	s_nop 0
	s_add_u32 s10, s44, 0x80
	s_addc_u32 s11, s45, 0
	global_load_lds_dwordx4 v128, s[10:11]
	s_mov_b32 m0, s54
	s_nop 0
	global_load_lds_dwordx4 v132, s[10:11]
	s_waitcnt vmcnt(8)
	s_waitcnt lgkmcnt(0)
	s_barrier
	s_waitcnt lgkmcnt(0)
	v_mfma_f32_16x16x32_bf16 v[60:63], v[152:155], v[188:191], v[60:63]
	v_mfma_f32_16x16x32_bf16 v[56:59], v[160:163], v[188:191], v[56:59]
	v_mfma_f32_16x16x32_bf16 v[52:55], v[152:155], v[196:199], v[52:55]
	v_mfma_f32_16x16x32_bf16 v[44:47], v[160:163], v[196:199], v[44:47]
	v_mfma_f32_16x16x32_bf16 v[36:39], v[152:155], v[204:207], v[36:39]
	v_mfma_f32_16x16x32_bf16 v[28:31], v[160:163], v[204:207], v[28:31]
	v_mfma_f32_16x16x32_bf16 v[20:23], v[152:155], v[212:215], v[20:23]
	v_mfma_f32_16x16x32_bf16 v[12:15], v[160:163], v[212:215], v[12:15]
	v_mfma_f32_16x16x32_bf16 v[60:63], v[156:159], v[192:195], v[60:63]
	v_mfma_f32_16x16x32_bf16 v[56:59], v[164:167], v[192:195], v[56:59]
	v_mfma_f32_16x16x32_bf16 v[52:55], v[156:159], v[200:203], v[52:55]
	v_mfma_f32_16x16x32_bf16 v[44:47], v[164:167], v[200:203], v[44:47]
	v_mfma_f32_16x16x32_bf16 v[36:39], v[156:159], v[208:211], v[36:39]
	v_mfma_f32_16x16x32_bf16 v[28:31], v[164:167], v[208:211], v[28:31]
	v_mfma_f32_16x16x32_bf16 v[20:23], v[156:159], v[216:219], v[20:23]
	v_mfma_f32_16x16x32_bf16 v[12:15], v[164:167], v[216:219], v[12:15]
	v_mfma_f32_16x16x32_bf16 v[48:51], v[168:171], v[188:191], v[48:51]
	v_mfma_f32_16x16x32_bf16 v[40:43], v[180:183], v[188:191], v[40:43]
	v_mfma_f32_16x16x32_bf16 v[32:35], v[168:171], v[196:199], v[32:35]
	v_mfma_f32_16x16x32_bf16 v[24:27], v[180:183], v[196:199], v[24:27]
	v_mfma_f32_16x16x32_bf16 v[16:19], v[168:171], v[204:207], v[16:19]
	v_mfma_f32_16x16x32_bf16 v[8:11], v[180:183], v[204:207], v[8:11]
	v_mfma_f32_16x16x32_bf16 v[4:7], v[168:171], v[212:215], v[4:7]
	v_mfma_f32_16x16x32_bf16 v[0:3], v[180:183], v[212:215], v[0:3]
	v_mfma_f32_16x16x32_bf16 v[48:51], v[172:175], v[192:195], v[48:51]
	v_mfma_f32_16x16x32_bf16 v[40:43], v[184:187], v[192:195], v[40:43]
	v_mfma_f32_16x16x32_bf16 v[32:35], v[172:175], v[200:203], v[32:35]
	v_mfma_f32_16x16x32_bf16 v[24:27], v[184:187], v[200:203], v[24:27]
	v_mfma_f32_16x16x32_bf16 v[16:19], v[172:175], v[208:211], v[16:19]
	v_mfma_f32_16x16x32_bf16 v[8:11], v[184:187], v[208:211], v[8:11]
	v_mfma_f32_16x16x32_bf16 v[4:7], v[172:175], v[216:219], v[4:7]
	v_mfma_f32_16x16x32_bf16 v[0:3], v[184:187], v[216:219], v[0:3]
	s_barrier
; __device__ __forceinline__ unsigned cvt_pk_bf16(float lo, float hi) { unsigned r; asm volatile("v_cvt_pk_bf16_f32 %0, %1, %2" : "=v"(r) : "v"(lo), "v"(hi)); return r; }
; #define PG8_WAIT_V(n) asm volatile("s_waitcnt vmcnt(" #n ")" ::: "memory")
; #define PG8_BAR __builtin_amdgcn_s_barrier()
;     __device__ __forceinline__ void operator()(const f32x4 (&acc)[2][2][4][2], const Unit& u, int wr, int wc, int fr, int fq) const {
;         const int row0 = u.pm * BM + wr * 64 + fr; const int col0 = u.pn * BM + wc * 32 + 8 * fq;
; #pragma unroll
;         for (int ai = 0; ai < 2; ++ai)
; #pragma unroll
;             for (int m = 0; m < 4; ++m) { bf16_t* rowp = O + (size_t)(row0 + ai * HALF + m * 16) * ldc + col0;
; #pragma unroll
;                 for (int bj = 0; bj < 2; ++bj) { const f32x4 v0 = acc[ai][bj][m][0], v1 = acc[ai][bj][m][1];
;                     u32x4 w; w.x = cvt_pk_bf16(v0[0], v0[1]); w.y = cvt_pk_bf16(v0[2], v0[3]); w.z = cvt_pk_bf16(v1[0], v1[1]); w.w = cvt_pk_bf16(v1[2], v1[3]);
;                     *(u32x4*)(rowp + bj * HALF) = w; } }
;     }
; template <class Epi, class Sched, bool ALIGN_EPI = false, bool SP2 = false>
; __device__ __forceinline__ void gemm_phase(PG8_LAS unsigned char* lds, const Gemm g, const Sched& S, const Epi& E) {
;     ...
;         if constexpr (!Epi::AFTER_DRAIN) { E(acc, cur, wr, wc, fr, fq); S.done(cur); }
;         if (!has_next) break;
; #pragma unroll
;         for (int a = 0; a < 2; ++a)
; #pragma unroll
;             for (int b = 0; b < 2; ++b)
; #pragma unroll
;                 for (int m = 0; m < 4; ++m)
; #pragma unroll
;                     for (int n = 0; n < 2; ++n) acc[a][b][m][n] = (f32x4){0.f, 0.f, 0.f, 0.f};
;         cur = nxt; cA = nA; cB = nB; ++ui;
;         if constexpr (ALIGN_EPI) { if (wr == 1) PG8_BAR; }
;     }
;     PG8_WAIT_V(0);
;     if constexpr (!ALIGN_EPI) { if (wr == 0) PG8_BAR; }
	s_add_i32 s67, s67, 2
	s_add_u32 s65, s65, 0x100
	s_addc_u32 s66, s66, 0
	s_cmpk_gt_u32 s67, 0x55
	s_mov_b64 s[26:27], s[34:35]
	s_cbranch_scc0 .LBB0_552
	v_lshl_add_u32 v152, s63, 8, v146
	v_lshl_or_b32 v144, s64, 8, v148
	v_ashrrev_i32_e32 v153, 31, v152
	v_ashrrev_i32_e32 v145, 31, v144
	v_lshlrev_b64 v[154:155], 12, v[152:153]
	v_lshl_add_u64 v[154:155], s[90:91], 0, v[154:155]
	v_lshlrev_b64 v[156:157], 1, v[144:145]
	v_lshl_add_u64 v[144:145], v[154:155], 0, v[156:157]
	v_cvt_pk_bf16_f32 v124, v124, v125
	v_cvt_pk_bf16_f32 v125, v126, v127
	v_cvt_pk_bf16_f32 v126, v120, v121
	v_cvt_pk_bf16_f32 v127, v122, v123
	global_store_dwordx4 v[144:145], v[124:127], off
	v_cvt_pk_bf16_f32 v112, v112, v113
	v_cvt_pk_bf16_f32 v113, v114, v115
	v_cvt_pk_bf16_f32 v114, v104, v105
	v_or_b32_e32 v104, 16, v152
	v_ashrrev_i32_e32 v105, 31, v104
	v_lshlrev_b64 v[104:105], 12, v[104:105]
	v_lshl_add_u64 v[104:105], s[90:91], 0, v[104:105]
	v_cvt_pk_bf16_f32 v115, v106, v107
	global_store_dwordx4 v[144:145], v[112:115], off offset:256
	s_mov_b32 s64, s61
	s_mov_b32 s63, s62
	v_lshl_add_u64 v[112:113], v[104:105], 0, v[156:157]
	v_cvt_pk_bf16_f32 v104, v116, v117
	v_cvt_pk_bf16_f32 v105, v118, v119
	v_cvt_pk_bf16_f32 v106, v108, v109
	v_cvt_pk_bf16_f32 v107, v110, v111
	global_store_dwordx4 v[112:113], v[104:107], off
	v_cvt_pk_bf16_f32 v96, v96, v97
	v_cvt_pk_bf16_f32 v97, v98, v99
	v_cvt_pk_bf16_f32 v98, v88, v89
	v_or_b32_e32 v88, 32, v152
	v_ashrrev_i32_e32 v89, 31, v88
	v_lshlrev_b64 v[88:89], 12, v[88:89]
	v_lshl_add_u64 v[88:89], s[90:91], 0, v[88:89]
	v_cvt_pk_bf16_f32 v99, v90, v91
	global_store_dwordx4 v[112:113], v[96:99], off offset:256
	s_mov_b64 s[34:35], s[8:9]
	s_mov_b64 s[26:27], s[6:7]
	v_lshl_add_u64 v[96:97], v[88:89], 0, v[156:157]
	v_cvt_pk_bf16_f32 v88, v100, v101
	v_cvt_pk_bf16_f32 v89, v102, v103
	v_cvt_pk_bf16_f32 v90, v92, v93
	v_cvt_pk_bf16_f32 v91, v94, v95
	global_store_dwordx4 v[96:97], v[88:91], off
	v_cvt_pk_bf16_f32 v80, v80, v81
	v_cvt_pk_bf16_f32 v81, v82, v83
	v_cvt_pk_bf16_f32 v82, v72, v73
	v_or_b32_e32 v72, 48, v152
	v_ashrrev_i32_e32 v73, 31, v72
	v_lshlrev_b64 v[72:73], 12, v[72:73]
	v_lshl_add_u64 v[72:73], s[90:91], 0, v[72:73]
	v_cvt_pk_bf16_f32 v83, v74, v75
	global_store_dwordx4 v[96:97], v[80:83], off offset:256
	s_nop 1
	v_lshl_add_u64 v[80:81], v[72:73], 0, v[156:157]
	v_cvt_pk_bf16_f32 v72, v84, v85
	v_cvt_pk_bf16_f32 v73, v86, v87
	v_cvt_pk_bf16_f32 v74, v76, v77
	v_cvt_pk_bf16_f32 v75, v78, v79
	global_store_dwordx4 v[80:81], v[72:75], off
	v_cvt_pk_bf16_f32 v68, v68, v69
	v_cvt_pk_bf16_f32 v69, v70, v71
	v_cvt_pk_bf16_f32 v70, v64, v65
	v_cvt_pk_bf16_f32 v71, v66, v67
	global_store_dwordx4 v[80:81], v[68:71], off offset:256
	v_cvt_pk_bf16_f32 v60, v60, v61
	v_cvt_pk_bf16_f32 v61, v62, v63
	v_cvt_pk_bf16_f32 v62, v56, v57
	v_add_co_u32_e32 v56, vcc, s57, v144
	v_lshl_add_u64 v[64:65], v[144:145], 0, s[16:17]
	s_nop 0
	v_addc_co_u32_e32 v57, vcc, 0, v145, vcc
	v_cvt_pk_bf16_f32 v63, v58, v59
	global_store_dwordx4 v[56:57], v[60:63], off
	v_cvt_pk_bf16_f32 v48, v48, v49
	v_cvt_pk_bf16_f32 v49, v50, v51
	v_cvt_pk_bf16_f32 v50, v40, v41
	v_cvt_pk_bf16_f32 v51, v42, v43
	global_store_dwordx4 v[64:65], v[48:51], off offset:256
	v_cvt_pk_bf16_f32 v40, v52, v53
	v_cvt_pk_bf16_f32 v41, v54, v55
	v_cvt_pk_bf16_f32 v42, v44, v45
	v_add_co_u32_e32 v44, vcc, s58, v144
	s_nop 0
	v_lshl_add_u64 v[48:49], v[144:145], 0, s[20:21]
	v_addc_co_u32_e32 v45, vcc, 0, v145, vcc
	v_cvt_pk_bf16_f32 v43, v46, v47
	global_store_dwordx4 v[44:45], v[40:43], off
	v_cvt_pk_bf16_f32 v32, v32, v33
	v_cvt_pk_bf16_f32 v33, v34, v35
	v_cvt_pk_bf16_f32 v34, v24, v25
	v_cvt_pk_bf16_f32 v35, v26, v27
	global_store_dwordx4 v[48:49], v[32:35], off offset:256
	v_cvt_pk_bf16_f32 v24, v36, v37
	v_cvt_pk_bf16_f32 v25, v38, v39
	v_cvt_pk_bf16_f32 v26, v28, v29
	v_add_co_u32_e32 v28, vcc, s59, v144
	s_nop 0
	v_lshl_add_u64 v[32:33], v[144:145], 0, s[22:23]
	v_addc_co_u32_e32 v29, vcc, 0, v145, vcc
	v_cvt_pk_bf16_f32 v27, v30, v31
	global_store_dwordx4 v[28:29], v[24:27], off
	v_cvt_pk_bf16_f32 v16, v16, v17
	v_cvt_pk_bf16_f32 v17, v18, v19
	v_cvt_pk_bf16_f32 v18, v8, v9
	v_cvt_pk_bf16_f32 v19, v10, v11
	global_store_dwordx4 v[32:33], v[16:19], off offset:256
	v_cvt_pk_bf16_f32 v8, v20, v21
	v_cvt_pk_bf16_f32 v9, v22, v23
	v_cvt_pk_bf16_f32 v10, v12, v13
	v_add_co_u32_e32 v12, vcc, s60, v144
	s_nop 0
	v_lshl_add_u64 v[16:17], v[144:145], 0, s[24:25]
	v_addc_co_u32_e32 v13, vcc, 0, v145, vcc
	s_and_b64 vcc, exec, s[4:5]
	v_cvt_pk_bf16_f32 v11, v14, v15
	global_store_dwordx4 v[12:13], v[8:11], off
	v_cvt_pk_bf16_f32 v4, v4, v5
	v_cvt_pk_bf16_f32 v5, v6, v7
	v_cvt_pk_bf16_f32 v6, v0, v1
	v_cvt_pk_bf16_f32 v7, v2, v3
	global_store_dwordx4 v[16:17], v[4:7], off offset:256
	s_cbranch_vccz .LBB0_541
	s_waitcnt vmcnt(0)
	s_cmpk_gt_u32 s0, 0xff
	s_cbranch_scc1 .LBB0_556
	s_barrier
